# P9/P17 epilogue: packed bf16 blocks lane-transposed through per-wave LDS slot so consecutive lanes store consecutive 16B pieces
# baseline (speedup 1.0000x reference)
.LBB0_773:
	s_or_b64 exec, exec, s[0:1]
	v_mov_b32_e32 v8, v168
	s_waitcnt lgkmcnt(0)
	s_barrier
	v_and_b32_e32 v244, 63, v168
	v_and_b32_e32 v245, 15, v244
	v_lshrrev_b32_e32 v246, 4, v244
	v_lshrrev_b32_e32 v247, 6, v168
	v_bfe_u32 v248, v245, 1, 2
	v_xor_b32_e32 v248, v248, v246
	v_lshlrev_b32_e32 v248, 4, v248
	v_lshl_add_u32 v248, v245, 6, v248
	v_lshl_add_u32 v248, v247, 11, v248
	v_add_u32_e32 v248, 0x22410, v248
	v_bfe_u32 v249, v244, 3, 2
	v_and_b32_e32 v252, 3, v244
	v_xor_b32_e32 v249, v249, v252
	v_lshlrev_b32_e32 v249, 4, v249
	v_lshrrev_b32_e32 v253, 2, v244
	v_lshl_add_u32 v249, v253, 6, v249
	v_lshl_add_u32 v249, v247, 11, v249
	v_add_u32_e32 v249, 0x22410, v249
	v_sub_u32_e32 v250, v253, v245
	v_sub_u32_e32 v251, v252, v246
	v_lshlrev_b32_e32 v251, 4, v251
	v_lshl_add_u32 v250, v250, 13, v251
	v_ashrrev_i32_e32 v251, 31, v250
	s_cmpk_lt_i32 s69, 0x1080
	s_nop 0
	v_readfirstlane_b32 s33, v8
	s_cbranch_scc0 .LBB0_795
	v_readlane_b32 s0, v242, 18
	v_readlane_b32 s1, v242, 19
	s_movk_i32 s34, 0x211
	s_and_b64 s[0:1], s[0:1], exec
	s_cselect_b32 s0, s34, 0x210
	v_readlane_b32 s1, v242, 20
	s_mul_i32 s0, s0, s1
	v_readlane_b32 s1, v242, 17
	s_add_i32 s0, s0, s1
	v_lshlrev_b32_e32 v10, 4, v8
	s_ashr_i32 s1, s0, 31
	v_add_u32_e32 v0, 0x2000, v10
	s_lshr_b32 s1, s1, 25
	v_ashrrev_i32_e32 v1, 31, v0
	s_add_i32 s1, s0, s1
	v_lshrrev_b32_e32 v1, 22, v1
	s_ashr_i32 s4, s1, 7
	s_and_b32 s1, s1, 0xff80
	v_add_u32_e32 v1, v0, v1
	s_sub_i32 s0, s0, s1
	v_ashrrev_i32_e32 v9, 10, v1
	s_bfe_i32 s1, s0, 0x80000
	v_mul_i32_i24_e32 v1, 0x400, v9
	s_bfe_u32 s1, s1, 0x3000c
	v_sub_u32_e32 v0, v0, v1
	s_add_i32 s1, s0, s1
	v_lshrrev_b32_e32 v1, 4, v0
	s_lshl_b32 s5, s4, 3
	s_bfe_i32 s4, s1, 0x80000
	s_and_b32 s1, s1, 0xf8
	v_bitop3_b32 v0, v1, v0, 32 bitop3:0x6c
	s_sub_i32 s0, s0, s1
	v_ashrrev_i32_e32 v1, 31, v0
	s_sext_i32_i16 s4, s4
	s_sext_i32_i8 s0, s0
	v_lshrrev_b32_e32 v1, 26, v1
	s_lshr_b32 s4, s4, 3
	s_add_i32 s24, s5, s0
	v_add_u32_e32 v1, v0, v1
	v_lshlrev_b32_e32 v2, 3, v9
	s_ashr_i32 s25, s24, 31
	s_bfe_i64 s[6:7], s[4:5], 0x100000
	v_ashrrev_i32_e32 v11, 6, v1
	v_and_b32_e32 v2, -16, v2
	s_lshl_b64 s[0:1], s[24:25], 19
	s_lshl_b64 s[6:7], s[6:7], 19
	v_readlane_b32 s14, v243, 39
	v_add_u32_e32 v2, v11, v2
	s_add_u32 s28, s14, s6
	v_and_b32_e32 v3, 3, v11
	s_mov_b32 s14, 0x1fffe0
	v_lshrrev_b32_e32 v4, 2, v2
	v_lshlrev_b32_e32 v5, 1, v2
	v_and_b32_e32 v1, 0xc0, v1
	v_and_or_b32 v3, v2, s14, v3
	v_and_b32_e32 v4, 4, v4
	v_and_b32_e32 v5, 24, v5
	v_sub_u32_e32 v0, v0, v1
	v_mov_b32_e32 v1, 1
	v_or3_b32 v3, v3, v4, v5
	v_lshlrev_b32_e32 v4, 5, v9
	v_ashrrev_i16_sdwa v0, v1, sext(v0) dst_sel:DWORD dst_unused:UNUSED_PAD src0_sel:DWORD src1_sel:BYTE_0
	v_and_b32_e32 v4, 32, v4
	v_bfe_i32 v12, v0, 0, 16
	v_add_lshl_u32 v0, v4, v12, 1
	v_lshl_add_u32 v144, v3, 11, v0
	v_lshl_add_u32 v146, v2, 11, v0
	v_bfe_i32 v0, v8, 27, 1
	v_lshrrev_b32_e32 v0, 22, v0
	v_add_u32_e32 v0, v10, v0
	v_ashrrev_i32_e32 v13, 10, v0
	v_mul_i32_i24_e32 v0, 0x400, v13
	v_sub_u32_e32 v0, v10, v0
	v_lshrrev_b32_e32 v2, 4, v0
	v_bitop3_b32 v0, v2, v0, 32 bitop3:0x6c
	v_ashrrev_i32_e32 v2, 31, v0
	v_readlane_b32 s15, v243, 40
	v_lshrrev_b32_e32 v2, 26, v2
	s_addc_u32 s29, s15, s7
	v_add_u32_e32 v2, v0, v2
	v_lshlrev_b32_e32 v3, 3, v13
	s_add_u32 s26, s8, s0
	v_ashrrev_i32_e32 v14, 6, v2
	v_and_b32_e32 v3, -16, v3
	s_addc_u32 s27, s9, s1
	s_ashr_i32 s25, s33, 6
	v_add_u32_e32 v3, v14, v3
	s_ashr_i32 s5, s33, 8
	s_lshl_b32 s35, s25, 10
	v_and_b32_e32 v4, 3, v14
	v_lshrrev_b32_e32 v5, 2, v3
	v_lshlrev_b32_e32 v6, 1, v3
	v_and_b32_e32 v2, 0xc0, v2
	s_add_u32 s0, s26, 0x40000
	v_and_or_b32 v4, v3, s14, v4
	v_and_b32_e32 v5, 4, v5
	v_and_b32_e32 v6, 24, v6
	v_sub_u32_e32 v0, v0, v2
	s_addc_u32 s1, s27, 0
	v_or3_b32 v4, v4, v5, v6
	v_lshlrev_b32_e32 v5, 5, v13
	v_ashrrev_i16_sdwa v0, v1, sext(v0) dst_sel:DWORD dst_unused:UNUSED_PAD src0_sel:DWORD src1_sel:BYTE_0
	s_add_u32 s6, s28, 0x40000
	v_and_b32_e32 v5, 32, v5
	v_bfe_i32 v15, v0, 0, 16
	s_addc_u32 s7, s29, 0
	v_add_lshl_u32 v0, v5, v15, 1
	s_add_i32 s36, s35, 0
	v_lshl_add_u32 v148, v4, 11, v0
	s_add_i32 m0, s36, 0x10000
	v_lshl_add_u32 v150, v3, 11, v0
	global_load_lds_dwordx4 v148, s[28:29]
	s_add_i32 m0, s36, 0x12000
	s_add_i32 s37, s36, 0x2000
	global_load_lds_dwordx4 v144, s[28:29]
	s_mov_b32 m0, s36
	s_add_i32 s38, s36, 0x4000
	global_load_lds_dwordx4 v150, s[26:27]
	s_mov_b32 m0, s37
	s_add_i32 s39, s36, 0x6000
	global_load_lds_dwordx4 v146, s[26:27]
	s_add_i32 m0, s36, 0x14000
	v_mov_b32_e32 v149, 0
	global_load_lds_dwordx4 v148, s[6:7]
	s_add_i32 m0, s36, 0x16000
	v_mov_b32_e32 v145, v149
	global_load_lds_dwordx4 v144, s[6:7]
	s_mov_b32 m0, s38
	v_mov_b32_e32 v151, v149
	global_load_lds_dwordx4 v150, s[0:1]
	s_mov_b32 m0, s39
	v_mov_b32_e32 v147, v149
	global_load_lds_dwordx4 v146, s[0:1]
	s_mov_b32 s17, 0
	v_lshl_add_u64 v[6:7], s[28:29], 0, v[148:149]
	v_lshl_add_u64 v[4:5], s[28:29], 0, v[144:145]
	v_lshl_add_u64 v[2:3], s[26:27], 0, v[150:151]
	s_cmp_lg_u32 s5, 1
	v_lshl_add_u64 v[0:1], s[26:27], 0, v[146:147]
	s_cbranch_scc1 .LBB0_776
	s_barrier

.LBB0_790:
	ds_read_b128 v[128:131], v174
	ds_read_b128 v[132:135], v174 offset:1024
	ds_read_b128 v[136:139], v174 offset:2048
	ds_read_b128 v[140:143], v174 offset:3072
	s_add_u32 s28, s26, 0xfffc0080
	s_addc_u32 s29, s27, -1
	s_cmp_eq_u32 s51, 12
	s_cselect_b32 s31, s19, s29
	s_cselect_b32 s30, s47, s28
	s_cselect_b32 s29, s17, s50
	s_cselect_b32 s28, s48, s49
	v_lshl_add_u64 v[164:165], s[26:27], 0, v[152:153]
	s_add_i32 m0, s36, 0xc000
	ds_read_b128 v[160:163], v175
	ds_read_b128 v[178:181], v175 offset:1024
	ds_read_b128 v[182:185], v175 offset:2048
	ds_read_b128 v[186:189], v175 offset:3072
	ds_read_b128 v[190:193], v175 offset:4096
	ds_read_b128 v[194:197], v175 offset:5120
	ds_read_b128 v[198:201], v175 offset:6144
	ds_read_b128 v[202:205], v175 offset:7168
	global_load_lds_dwordx4 v[164:165], off
	v_lshl_add_u64 v[164:165], s[26:27], 0, v[154:155]
	s_add_i32 m0, s36, 0xe000
	s_nop 0
	global_load_lds_dwordx4 v[164:165], off
	s_waitcnt lgkmcnt(8)
	s_barrier
	s_waitcnt lgkmcnt(0)
	s_setprio 1
	s_waitcnt lgkmcnt(0)
	v_mfma_f32_16x16x32_bf16 v[124:127], v[128:131], v[160:163], v[124:127]
	v_mfma_f32_16x16x32_bf16 v[120:123], v[136:139], v[160:163], v[120:123]
	v_mfma_f32_16x16x32_bf16 v[108:111], v[128:131], v[182:185], v[108:111]
	v_mfma_f32_16x16x32_bf16 v[104:107], v[136:139], v[182:185], v[104:107]
	v_mfma_f32_16x16x32_bf16 v[92:95], v[128:131], v[190:193], v[92:95]
	v_mfma_f32_16x16x32_bf16 v[88:91], v[136:139], v[190:193], v[88:91]
	v_mfma_f32_16x16x32_bf16 v[76:79], v[128:131], v[198:201], v[76:79]
	v_mfma_f32_16x16x32_bf16 v[72:75], v[136:139], v[198:201], v[72:75]
	v_mfma_f32_16x16x32_bf16 v[124:127], v[132:135], v[178:181], v[124:127]
	v_mfma_f32_16x16x32_bf16 v[120:123], v[140:143], v[178:181], v[120:123]
	v_mfma_f32_16x16x32_bf16 v[108:111], v[132:135], v[186:189], v[108:111]
	v_mfma_f32_16x16x32_bf16 v[104:107], v[140:143], v[186:189], v[104:107]
	v_mfma_f32_16x16x32_bf16 v[92:95], v[132:135], v[194:197], v[92:95]
	v_mfma_f32_16x16x32_bf16 v[88:91], v[140:143], v[194:197], v[88:91]
	v_mfma_f32_16x16x32_bf16 v[76:79], v[132:135], v[202:205], v[76:79]
	v_mfma_f32_16x16x32_bf16 v[72:75], v[140:143], v[202:205], v[72:75]
	s_setprio 0
	s_barrier
	s_add_i32 s52, s42, s35
	v_lshl_add_u64 v[164:165], s[28:29], 0, v[148:149]
	s_mov_b32 m0, s52
	ds_read_b128 v[206:209], v176
	ds_read_b128 v[210:213], v176 offset:1024
	ds_read_b128 v[214:217], v176 offset:2048
	ds_read_b128 v[218:221], v176 offset:3072
	global_load_lds_dwordx4 v[164:165], off
	v_lshl_add_u64 v[222:223], s[28:29], 0, v[144:145]
	s_add_i32 m0, s52, 0x2000
	s_nop 0
	global_load_lds_dwordx4 v[222:223], off
	s_barrier
	s_waitcnt lgkmcnt(0)
	s_setprio 1
	s_waitcnt lgkmcnt(0)
	v_mfma_f32_16x16x32_bf16 v[116:119], v[206:209], v[160:163], v[116:119]
	v_mfma_f32_16x16x32_bf16 v[112:115], v[214:217], v[160:163], v[112:115]
	v_mfma_f32_16x16x32_bf16 v[100:103], v[206:209], v[182:185], v[100:103]
	v_mfma_f32_16x16x32_bf16 v[96:99], v[214:217], v[182:185], v[96:99]
	v_mfma_f32_16x16x32_bf16 v[84:87], v[206:209], v[190:193], v[84:87]
	v_mfma_f32_16x16x32_bf16 v[80:83], v[214:217], v[190:193], v[80:83]
	v_mfma_f32_16x16x32_bf16 v[68:71], v[206:209], v[198:201], v[68:71]
	v_mfma_f32_16x16x32_bf16 v[64:67], v[214:217], v[198:201], v[64:67]
	v_mfma_f32_16x16x32_bf16 v[116:119], v[210:213], v[178:181], v[116:119]
	v_mfma_f32_16x16x32_bf16 v[112:115], v[218:221], v[178:181], v[112:115]
	v_mfma_f32_16x16x32_bf16 v[100:103], v[210:213], v[186:189], v[100:103]
	v_mfma_f32_16x16x32_bf16 v[96:99], v[218:221], v[186:189], v[96:99]
	v_mfma_f32_16x16x32_bf16 v[84:87], v[210:213], v[194:197], v[84:87]
	v_mfma_f32_16x16x32_bf16 v[80:83], v[218:221], v[194:197], v[80:83]
	v_mfma_f32_16x16x32_bf16 v[68:71], v[210:213], v[202:205], v[68:71]
	v_mfma_f32_16x16x32_bf16 v[64:67], v[218:221], v[202:205], v[64:67]
	s_setprio 0
	s_mov_b32 m0, s36
	v_lshl_add_u64 v[224:225], s[30:31], 0, v[150:151]
	s_barrier
	ds_read_b128 v[160:163], v175 offset:16384
	ds_read_b128 v[178:181], v175 offset:17408
	ds_read_b128 v[182:185], v175 offset:18432
	ds_read_b128 v[186:189], v175 offset:19456
	ds_read_b128 v[190:193], v175 offset:20480
	ds_read_b128 v[194:197], v175 offset:21504
	ds_read_b128 v[198:201], v175 offset:22528
	ds_read_b128 v[202:205], v175 offset:23552
	global_load_lds_dwordx4 v[224:225], off
	v_lshl_add_u64 v[226:227], s[30:31], 0, v[146:147]
	s_mov_b32 m0, s37
	s_nop 0
	global_load_lds_dwordx4 v[226:227], off
	s_barrier
	s_waitcnt lgkmcnt(0)
	s_setprio 1
	s_waitcnt lgkmcnt(0)
	v_mfma_f32_16x16x32_bf16 v[60:63], v[128:131], v[160:163], v[60:63]
	v_mfma_f32_16x16x32_bf16 v[56:59], v[136:139], v[160:163], v[56:59]
	v_mfma_f32_16x16x32_bf16 v[44:47], v[128:131], v[182:185], v[44:47]
	v_mfma_f32_16x16x32_bf16 v[40:43], v[136:139], v[182:185], v[40:43]
	v_mfma_f32_16x16x32_bf16 v[28:31], v[128:131], v[190:193], v[28:31]
	v_mfma_f32_16x16x32_bf16 v[24:27], v[136:139], v[190:193], v[24:27]
	v_mfma_f32_16x16x32_bf16 v[12:15], v[128:131], v[198:201], v[12:15]
	v_mfma_f32_16x16x32_bf16 v[8:11], v[136:139], v[198:201], v[8:11]
	v_mfma_f32_16x16x32_bf16 v[60:63], v[132:135], v[178:181], v[60:63]
	v_mfma_f32_16x16x32_bf16 v[56:59], v[140:143], v[178:181], v[56:59]
	v_mfma_f32_16x16x32_bf16 v[44:47], v[132:135], v[186:189], v[44:47]
	v_mfma_f32_16x16x32_bf16 v[40:43], v[140:143], v[186:189], v[40:43]
	v_mfma_f32_16x16x32_bf16 v[28:31], v[132:135], v[194:197], v[28:31]
	v_mfma_f32_16x16x32_bf16 v[24:27], v[140:143], v[194:197], v[24:27]
	v_mfma_f32_16x16x32_bf16 v[12:15], v[132:135], v[202:205], v[12:15]
	v_mfma_f32_16x16x32_bf16 v[8:11], v[140:143], v[202:205], v[8:11]
	s_setprio 0
	s_barrier
	s_add_u32 s52, s28, 0x40000
	s_addc_u32 s53, s29, 0
	s_add_i32 s54, s43, s35
	v_lshl_add_u64 v[128:129], s[52:53], 0, v[148:149]
	s_mov_b32 m0, s54
	s_nop 0
	global_load_lds_dwordx4 v[128:129], off
	v_lshl_add_u64 v[128:129], s[52:53], 0, v[144:145]
	s_add_i32 m0, s54, 0x2000
	s_nop 0
	global_load_lds_dwordx4 v[128:129], off
	s_waitcnt vmcnt(6)
	s_barrier
	s_setprio 1
	v_mfma_f32_16x16x32_bf16 v[52:55], v[206:209], v[160:163], v[52:55]
	v_mfma_f32_16x16x32_bf16 v[48:51], v[214:217], v[160:163], v[48:51]
	v_mfma_f32_16x16x32_bf16 v[36:39], v[206:209], v[182:185], v[36:39]
	v_mfma_f32_16x16x32_bf16 v[32:35], v[214:217], v[182:185], v[32:35]
	v_mfma_f32_16x16x32_bf16 v[20:23], v[206:209], v[190:193], v[20:23]
	v_mfma_f32_16x16x32_bf16 v[16:19], v[214:217], v[190:193], v[16:19]
	v_mfma_f32_16x16x32_bf16 v[4:7], v[206:209], v[198:201], v[4:7]
	v_mfma_f32_16x16x32_bf16 v[0:3], v[214:217], v[198:201], v[0:3]
	v_mfma_f32_16x16x32_bf16 v[52:55], v[210:213], v[178:181], v[52:55]
	v_mfma_f32_16x16x32_bf16 v[48:51], v[218:221], v[178:181], v[48:51]
	v_mfma_f32_16x16x32_bf16 v[36:39], v[210:213], v[186:189], v[36:39]
	v_mfma_f32_16x16x32_bf16 v[32:35], v[218:221], v[186:189], v[32:35]
	v_mfma_f32_16x16x32_bf16 v[20:23], v[210:213], v[194:197], v[20:23]
	v_mfma_f32_16x16x32_bf16 v[16:19], v[218:221], v[194:197], v[16:19]
	v_mfma_f32_16x16x32_bf16 v[4:7], v[210:213], v[202:205], v[4:7]
	v_mfma_f32_16x16x32_bf16 v[0:3], v[218:221], v[202:205], v[0:3]
	s_setprio 0
	s_add_i32 s52, 0, 0x18000
	v_add_u32_e32 v140, s52, v170
	s_barrier
	ds_read_b128 v[128:131], v140
	ds_read_b128 v[132:135], v140 offset:1024
	ds_read_b128 v[136:139], v140 offset:2048
	ds_read_b128 v[140:143], v140 offset:3072
	s_add_u32 s30, s30, 0x40000
	s_addc_u32 s31, s31, 0
	s_mov_b32 m0, s38
	v_lshl_add_u64 v[206:207], s[30:31], 0, v[150:151]
	ds_read_b128 v[160:163], v175 offset:32768
	ds_read_b128 v[178:181], v175 offset:33792
	ds_read_b128 v[182:185], v175 offset:34816
	ds_read_b128 v[186:189], v175 offset:35840
	ds_read_b128 v[190:193], v175 offset:36864
	ds_read_b128 v[194:197], v175 offset:37888
	ds_read_b128 v[198:201], v175 offset:38912
	ds_read_b128 v[202:205], v175 offset:39936
	global_load_lds_dwordx4 v[206:207], off
	v_lshl_add_u64 v[206:207], s[30:31], 0, v[146:147]
	s_mov_b32 m0, s39
	s_nop 0
	global_load_lds_dwordx4 v[206:207], off
	s_waitcnt lgkmcnt(8)
	s_barrier
	s_waitcnt lgkmcnt(0)
	s_setprio 1
	s_waitcnt lgkmcnt(0)
	v_mfma_f32_16x16x32_bf16 v[124:127], v[128:131], v[160:163], v[124:127]
	v_mfma_f32_16x16x32_bf16 v[120:123], v[136:139], v[160:163], v[120:123]
	v_mfma_f32_16x16x32_bf16 v[108:111], v[128:131], v[182:185], v[108:111]
	v_mfma_f32_16x16x32_bf16 v[104:107], v[136:139], v[182:185], v[104:107]
	v_mfma_f32_16x16x32_bf16 v[92:95], v[128:131], v[190:193], v[92:95]
	v_mfma_f32_16x16x32_bf16 v[88:91], v[136:139], v[190:193], v[88:91]
	v_mfma_f32_16x16x32_bf16 v[76:79], v[128:131], v[198:201], v[76:79]
	v_mfma_f32_16x16x32_bf16 v[72:75], v[136:139], v[198:201], v[72:75]
	v_mfma_f32_16x16x32_bf16 v[124:127], v[132:135], v[178:181], v[124:127]
	v_mfma_f32_16x16x32_bf16 v[120:123], v[140:143], v[178:181], v[120:123]
	v_mfma_f32_16x16x32_bf16 v[108:111], v[132:135], v[186:189], v[108:111]
	v_mfma_f32_16x16x32_bf16 v[104:107], v[140:143], v[186:189], v[104:107]
	v_mfma_f32_16x16x32_bf16 v[92:95], v[132:135], v[194:197], v[92:95]
	v_mfma_f32_16x16x32_bf16 v[88:91], v[140:143], v[194:197], v[88:91]
	v_mfma_f32_16x16x32_bf16 v[76:79], v[132:135], v[202:205], v[76:79]
	v_mfma_f32_16x16x32_bf16 v[72:75], v[140:143], v[202:205], v[72:75]
	s_setprio 0
	s_barrier
	s_add_i32 s30, 0, 0x1c000
	s_add_i32 s31, s52, s35
	v_add_u32_e32 v177, s30, v170
	v_lshl_add_u64 v[164:165], v[164:165], 0, s[0:1]
	s_mov_b32 m0, s31
	ds_read_b128 v[206:209], v177
	ds_read_b128 v[210:213], v177 offset:1024
	ds_read_b128 v[214:217], v177 offset:2048
	ds_read_b128 v[218:221], v177 offset:3072
	global_load_lds_dwordx4 v[164:165], off
	v_lshl_add_u64 v[164:165], v[222:223], 0, s[0:1]
	s_add_i32 m0, s31, 0x2000
	s_nop 0
	global_load_lds_dwordx4 v[164:165], off
	s_barrier
	s_waitcnt lgkmcnt(0)
	s_setprio 1
	s_waitcnt lgkmcnt(0)
	v_mfma_f32_16x16x32_bf16 v[116:119], v[206:209], v[160:163], v[116:119]
	v_mfma_f32_16x16x32_bf16 v[112:115], v[214:217], v[160:163], v[112:115]
	v_mfma_f32_16x16x32_bf16 v[100:103], v[206:209], v[182:185], v[100:103]
	v_mfma_f32_16x16x32_bf16 v[96:99], v[214:217], v[182:185], v[96:99]
	v_mfma_f32_16x16x32_bf16 v[84:87], v[206:209], v[190:193], v[84:87]
	v_mfma_f32_16x16x32_bf16 v[80:83], v[214:217], v[190:193], v[80:83]
	v_mfma_f32_16x16x32_bf16 v[68:71], v[206:209], v[198:201], v[68:71]
	v_mfma_f32_16x16x32_bf16 v[64:67], v[214:217], v[198:201], v[64:67]
	v_mfma_f32_16x16x32_bf16 v[116:119], v[210:213], v[178:181], v[116:119]
	v_mfma_f32_16x16x32_bf16 v[112:115], v[218:221], v[178:181], v[112:115]
	v_mfma_f32_16x16x32_bf16 v[100:103], v[210:213], v[186:189], v[100:103]
	v_mfma_f32_16x16x32_bf16 v[96:99], v[218:221], v[186:189], v[96:99]
	v_mfma_f32_16x16x32_bf16 v[84:87], v[210:213], v[194:197], v[84:87]
	v_mfma_f32_16x16x32_bf16 v[80:83], v[218:221], v[194:197], v[80:83]
	v_mfma_f32_16x16x32_bf16 v[68:71], v[210:213], v[202:205], v[68:71]
	v_mfma_f32_16x16x32_bf16 v[64:67], v[218:221], v[202:205], v[64:67]
	s_setprio 0
	s_mov_b32 m0, s40
	v_lshl_add_u64 v[164:165], v[224:225], 0, s[0:1]
	s_barrier
	ds_read_b128 v[160:163], v175 offset:49152
	ds_read_b128 v[178:181], v175 offset:50176
	ds_read_b128 v[182:185], v175 offset:51200
	ds_read_b128 v[186:189], v175 offset:52224
	ds_read_b128 v[190:193], v175 offset:53248
	ds_read_b128 v[194:197], v175 offset:54272
	ds_read_b128 v[198:201], v175 offset:55296
	ds_read_b128 v[202:205], v175 offset:56320
	global_load_lds_dwordx4 v[164:165], off
	v_lshl_add_u64 v[164:165], v[226:227], 0, s[0:1]
	s_mov_b32 m0, s41
	s_nop 0
	global_load_lds_dwordx4 v[164:165], off
	s_barrier
	s_waitcnt lgkmcnt(0)
	s_setprio 1
	s_waitcnt lgkmcnt(0)
	v_mfma_f32_16x16x32_bf16 v[60:63], v[128:131], v[160:163], v[60:63]
	v_mfma_f32_16x16x32_bf16 v[56:59], v[136:139], v[160:163], v[56:59]
	v_mfma_f32_16x16x32_bf16 v[44:47], v[128:131], v[182:185], v[44:47]
	v_mfma_f32_16x16x32_bf16 v[40:43], v[136:139], v[182:185], v[40:43]
	v_mfma_f32_16x16x32_bf16 v[28:31], v[128:131], v[190:193], v[28:31]
	v_mfma_f32_16x16x32_bf16 v[24:27], v[136:139], v[190:193], v[24:27]
	v_mfma_f32_16x16x32_bf16 v[12:15], v[128:131], v[198:201], v[12:15]
	v_mfma_f32_16x16x32_bf16 v[8:11], v[136:139], v[198:201], v[8:11]
	v_mfma_f32_16x16x32_bf16 v[60:63], v[132:135], v[178:181], v[60:63]
	v_mfma_f32_16x16x32_bf16 v[56:59], v[140:143], v[178:181], v[56:59]
	v_mfma_f32_16x16x32_bf16 v[44:47], v[132:135], v[186:189], v[44:47]
	v_mfma_f32_16x16x32_bf16 v[40:43], v[140:143], v[186:189], v[40:43]
	v_mfma_f32_16x16x32_bf16 v[28:31], v[132:135], v[194:197], v[28:31]
	v_mfma_f32_16x16x32_bf16 v[24:27], v[140:143], v[194:197], v[24:27]
	v_mfma_f32_16x16x32_bf16 v[12:15], v[132:135], v[202:205], v[12:15]
	v_mfma_f32_16x16x32_bf16 v[8:11], v[140:143], v[202:205], v[8:11]
	s_setprio 0
	s_barrier
	s_add_u32 s28, s28, 0x40080
	s_addc_u32 s29, s29, 0
	s_add_i32 s30, s30, s35
	v_lshl_add_u64 v[128:129], s[28:29], 0, v[148:149]
	s_mov_b32 m0, s30
	s_nop 0
	global_load_lds_dwordx4 v[128:129], off
	v_lshl_add_u64 v[128:129], s[28:29], 0, v[144:145]
	s_add_i32 m0, s30, 0x2000
	s_nop 0
	global_load_lds_dwordx4 v[128:129], off
	s_waitcnt vmcnt(6)
	s_barrier
	s_setprio 1
	v_mfma_f32_16x16x32_bf16 v[52:55], v[206:209], v[160:163], v[52:55]
	v_mfma_f32_16x16x32_bf16 v[48:51], v[214:217], v[160:163], v[48:51]
	v_mfma_f32_16x16x32_bf16 v[36:39], v[206:209], v[182:185], v[36:39]
	v_mfma_f32_16x16x32_bf16 v[32:35], v[214:217], v[182:185], v[32:35]
	v_mfma_f32_16x16x32_bf16 v[20:23], v[206:209], v[190:193], v[20:23]
	v_mfma_f32_16x16x32_bf16 v[16:19], v[214:217], v[190:193], v[16:19]
	v_mfma_f32_16x16x32_bf16 v[4:7], v[206:209], v[198:201], v[4:7]
	v_mfma_f32_16x16x32_bf16 v[0:3], v[214:217], v[198:201], v[0:3]
	v_mfma_f32_16x16x32_bf16 v[52:55], v[210:213], v[178:181], v[52:55]
	v_mfma_f32_16x16x32_bf16 v[48:51], v[218:221], v[178:181], v[48:51]
	v_mfma_f32_16x16x32_bf16 v[36:39], v[210:213], v[186:189], v[36:39]
	v_mfma_f32_16x16x32_bf16 v[32:35], v[218:221], v[186:189], v[32:35]
	v_mfma_f32_16x16x32_bf16 v[20:23], v[210:213], v[194:197], v[20:23]
	v_mfma_f32_16x16x32_bf16 v[16:19], v[218:221], v[194:197], v[16:19]
	v_mfma_f32_16x16x32_bf16 v[4:7], v[210:213], v[202:205], v[4:7]
	v_mfma_f32_16x16x32_bf16 v[0:3], v[218:221], v[202:205], v[0:3]
	s_setprio 0
	s_add_i32 s51, s51, 2
	s_add_u32 s26, s26, 0x100
	s_addc_u32 s27, s27, 0
	s_add_u32 s49, s49, 0x100
	s_addc_u32 s50, s50, 0
	s_cmp_gt_u32 s51, 13
	s_barrier
	s_cbranch_scc0 .LBB0_790
	v_add_u32_e32 v164, s46, v167
	v_add_u32_e32 v128, s46, v173
	v_add_u32_e32 v177, 0x400, v164
	ds_read_b128 v[140:143], v128
	ds_read_b128 v[136:139], v128 offset:16
	ds_read_b128 v[132:135], v128 offset:512
	ds_read_b128 v[128:131], v128 offset:528
	ds_read2_b32 v[178:179], v177 offset1:16
	v_lshl_add_u32 v162, s24, 8, v166
	v_lshl_or_b32 v160, s45, 8, v172
	v_ashrrev_i32_e32 v163, 31, v162
	v_readlane_b32 s26, v243, 56
	v_ashrrev_i32_e32 v161, 31, v160
	v_lshlrev_b64 v[164:165], 13, v[162:163]
	v_readlane_b32 s27, v243, 57
	s_waitcnt lgkmcnt(0)
	v_pk_fma_f32 v[120:121], v[120:121], v[178:179], v[136:137] op_sel_hi:[1,0,1]
	v_pk_fma_f32 v[126:127], v[126:127], v[178:179], v[142:143] op_sel_hi:[1,0,1]
	v_lshl_add_u64 v[180:181], s[26:27], 0, v[164:165]
	v_lshlrev_b64 v[164:165], 1, v[160:161]
	v_pk_fma_f32 v[124:125], v[124:125], v[178:179], v[140:141] op_sel_hi:[1,0,1]
	v_pk_fma_f32 v[122:123], v[122:123], v[178:179], v[138:139] op_sel_hi:[1,0,1]
	v_max_f32_e32 v120, 0, v120
	v_max_f32_e32 v121, 0, v121
	v_lshl_add_u64 v[160:161], v[180:181], 0, v[164:165]
	v_max_f32_e32 v124, 0, v124
	v_max_f32_e32 v125, 0, v125
	v_pk_mul_f32 v[180:181], v[120:121], v[120:121]
	v_max_f32_e32 v120, 0, v126
	v_max_f32_e32 v122, 0, v122
	v_max_f32_e32 v121, 0, v127
	v_max_f32_e32 v123, 0, v123
	v_pk_mul_f32 v[124:125], v[124:125], v[124:125]
	v_pk_mul_f32 v[126:127], v[120:121], v[120:121]
	v_pk_mul_f32 v[182:183], v[122:123], v[122:123]
	v_pk_fma_f32 v[112:113], v[112:113], v[178:179], v[128:129] op_sel_hi:[1,0,1]
	v_cvt_pk_bf16_f32 v120, v124, v125
	v_cvt_pk_bf16_f32 v121, v126, v127
	v_cvt_pk_bf16_f32 v122, v180, v181
	v_cvt_pk_bf16_f32 v123, v182, v183
	v_pk_fma_f32 v[118:119], v[118:119], v[178:179], v[134:135] op_sel_hi:[1,0,1]
	v_pk_fma_f32 v[116:117], v[116:117], v[178:179], v[132:133] op_sel_hi:[1,0,1]
	v_pk_fma_f32 v[114:115], v[114:115], v[178:179], v[130:131] op_sel_hi:[1,0,1]
	v_max_f32_e32 v112, 0, v112
	v_max_f32_e32 v113, 0, v113
	ds_write_b128 v248, v[120:123]
	v_lshl_add_u64 v[252:253], v[160:161], 0, v[250:251]
	v_max_f32_e32 v116, 0, v116
	v_max_f32_e32 v117, 0, v117
	v_pk_mul_f32 v[120:121], v[112:113], v[112:113]
	v_max_f32_e32 v112, 0, v118
	v_max_f32_e32 v114, 0, v114
	v_max_f32_e32 v113, 0, v119
	v_max_f32_e32 v115, 0, v115
	v_pk_mul_f32 v[116:117], v[116:117], v[116:117]
	v_pk_mul_f32 v[118:119], v[112:113], v[112:113]
	v_pk_mul_f32 v[122:123], v[114:115], v[114:115]
	v_cvt_pk_bf16_f32 v112, v116, v117
	v_cvt_pk_bf16_f32 v113, v118, v119
	v_cvt_pk_bf16_f32 v114, v120, v121
	v_cvt_pk_bf16_f32 v115, v122, v123
	ds_write_b128 v248, v[112:115] offset:1024
	v_lshl_add_u64 v[254:255], v[160:161], 0, v[250:251]
	s_waitcnt lgkmcnt(0)
	ds_read_b128 v[244:247], v249
	ds_read_b128 v[112:115], v249 offset:1024
	s_waitcnt lgkmcnt(1)
	global_store_dwordx4 v[252:253], v[244:247], off
	s_waitcnt lgkmcnt(0)
	global_store_dwordx4 v[254:255], v[112:115], off offset:256
	s_mov_b32 s17, 0x100000
	s_mov_b32 s45, s16
	v_mov_b32_e32 v114, v179
	v_or_b32_e32 v112, 16, v162
	v_pk_fma_f32 v[104:105], v[104:105], v[114:115], v[136:137] op_sel_hi:[1,0,1]
	v_ashrrev_i32_e32 v113, 31, v112
	v_pk_fma_f32 v[110:111], v[110:111], v[114:115], v[142:143] op_sel_hi:[1,0,1]
	v_pk_fma_f32 v[108:109], v[108:109], v[114:115], v[140:141] op_sel_hi:[1,0,1]
	v_pk_fma_f32 v[106:107], v[106:107], v[114:115], v[138:139] op_sel_hi:[1,0,1]
	v_max_f32_e32 v104, 0, v104
	v_max_f32_e32 v105, 0, v105
	v_lshlrev_b64 v[112:113], 13, v[112:113]
	v_max_f32_e32 v108, 0, v108
	v_max_f32_e32 v109, 0, v109
	v_pk_mul_f32 v[116:117], v[104:105], v[104:105]
	v_max_f32_e32 v104, 0, v110
	v_max_f32_e32 v106, 0, v106
	v_max_f32_e32 v105, 0, v111
	v_max_f32_e32 v107, 0, v107
	v_lshl_add_u64 v[112:113], s[26:27], 0, v[112:113]
	v_pk_mul_f32 v[108:109], v[108:109], v[108:109]
	v_pk_mul_f32 v[110:111], v[104:105], v[104:105]
	v_pk_mul_f32 v[118:119], v[106:107], v[106:107]
	v_pk_fma_f32 v[96:97], v[96:97], v[114:115], v[128:129] op_sel_hi:[1,0,1]
	v_lshl_add_u64 v[112:113], v[112:113], 0, v[164:165]
	v_cvt_pk_bf16_f32 v104, v108, v109
	v_cvt_pk_bf16_f32 v105, v110, v111
	v_cvt_pk_bf16_f32 v106, v116, v117
	v_cvt_pk_bf16_f32 v107, v118, v119
	v_pk_fma_f32 v[102:103], v[102:103], v[114:115], v[134:135] op_sel_hi:[1,0,1]
	v_pk_fma_f32 v[100:101], v[100:101], v[114:115], v[132:133] op_sel_hi:[1,0,1]
	v_pk_fma_f32 v[98:99], v[98:99], v[114:115], v[130:131] op_sel_hi:[1,0,1]
	v_max_f32_e32 v96, 0, v96
	v_max_f32_e32 v97, 0, v97
	ds_write_b128 v248, v[104:107]
	v_lshl_add_u64 v[252:253], v[112:113], 0, v[250:251]
	v_max_f32_e32 v100, 0, v100
	v_max_f32_e32 v101, 0, v101
	v_pk_mul_f32 v[104:105], v[96:97], v[96:97]
	v_max_f32_e32 v96, 0, v102
	v_max_f32_e32 v98, 0, v98
	v_max_f32_e32 v97, 0, v103
	v_max_f32_e32 v99, 0, v99
	v_pk_mul_f32 v[100:101], v[100:101], v[100:101]
	v_pk_mul_f32 v[102:103], v[96:97], v[96:97]
	v_pk_mul_f32 v[106:107], v[98:99], v[98:99]
	v_cvt_pk_bf16_f32 v96, v100, v101
	v_cvt_pk_bf16_f32 v97, v102, v103
	v_cvt_pk_bf16_f32 v98, v104, v105
	v_cvt_pk_bf16_f32 v99, v106, v107
	ds_write_b128 v248, v[96:99] offset:1024
	v_lshl_add_u64 v[254:255], v[112:113], 0, v[250:251]
	s_waitcnt lgkmcnt(0)
	ds_read_b128 v[244:247], v249
	ds_read_b128 v[96:99], v249 offset:1024
	s_waitcnt lgkmcnt(1)
	global_store_dwordx4 v[252:253], v[244:247], off
	s_waitcnt lgkmcnt(0)
	global_store_dwordx4 v[254:255], v[96:99], off offset:256
	ds_read2_b32 v[98:99], v177 offset0:32 offset1:48
	s_mov_b32 s24, s18
	v_or_b32_e32 v96, 32, v162
	v_ashrrev_i32_e32 v97, 31, v96
	v_lshlrev_b64 v[96:97], 13, v[96:97]
	s_waitcnt lgkmcnt(0)
	v_pk_fma_f32 v[88:89], v[88:89], v[98:99], v[136:137] op_sel_hi:[1,0,1]
	v_pk_fma_f32 v[94:95], v[94:95], v[98:99], v[142:143] op_sel_hi:[1,0,1]
	v_pk_fma_f32 v[92:93], v[92:93], v[98:99], v[140:141] op_sel_hi:[1,0,1]
	v_pk_fma_f32 v[90:91], v[90:91], v[98:99], v[138:139] op_sel_hi:[1,0,1]
	v_max_f32_e32 v88, 0, v88
	v_max_f32_e32 v89, 0, v89
	v_max_f32_e32 v92, 0, v92
	v_max_f32_e32 v93, 0, v93
	v_pk_mul_f32 v[100:101], v[88:89], v[88:89]
	v_max_f32_e32 v88, 0, v94
	v_max_f32_e32 v90, 0, v90
	v_max_f32_e32 v89, 0, v95
	v_max_f32_e32 v91, 0, v91
	v_lshl_add_u64 v[96:97], s[26:27], 0, v[96:97]
	v_pk_mul_f32 v[92:93], v[92:93], v[92:93]
	v_pk_mul_f32 v[94:95], v[88:89], v[88:89]
	v_pk_mul_f32 v[102:103], v[90:91], v[90:91]
	v_pk_fma_f32 v[80:81], v[80:81], v[98:99], v[128:129] op_sel_hi:[1,0,1]
	v_lshl_add_u64 v[96:97], v[96:97], 0, v[164:165]
	v_cvt_pk_bf16_f32 v88, v92, v93
	v_cvt_pk_bf16_f32 v89, v94, v95
	v_cvt_pk_bf16_f32 v90, v100, v101
	v_cvt_pk_bf16_f32 v91, v102, v103
	v_pk_fma_f32 v[86:87], v[86:87], v[98:99], v[134:135] op_sel_hi:[1,0,1]
	v_pk_fma_f32 v[84:85], v[84:85], v[98:99], v[132:133] op_sel_hi:[1,0,1]
	v_pk_fma_f32 v[82:83], v[82:83], v[98:99], v[130:131] op_sel_hi:[1,0,1]
	v_max_f32_e32 v80, 0, v80
	v_max_f32_e32 v81, 0, v81
	ds_write_b128 v248, v[88:91]
	v_lshl_add_u64 v[252:253], v[96:97], 0, v[250:251]
	v_max_f32_e32 v84, 0, v84
	v_max_f32_e32 v85, 0, v85
	v_pk_mul_f32 v[88:89], v[80:81], v[80:81]
	v_max_f32_e32 v80, 0, v86
	v_max_f32_e32 v82, 0, v82
	v_max_f32_e32 v81, 0, v87
	v_max_f32_e32 v83, 0, v83
	v_pk_mul_f32 v[84:85], v[84:85], v[84:85]
	v_pk_mul_f32 v[86:87], v[80:81], v[80:81]
	v_pk_mul_f32 v[90:91], v[82:83], v[82:83]
	v_cvt_pk_bf16_f32 v80, v84, v85
	v_cvt_pk_bf16_f32 v81, v86, v87
	v_cvt_pk_bf16_f32 v82, v88, v89
	v_cvt_pk_bf16_f32 v83, v90, v91
	ds_write_b128 v248, v[80:83] offset:1024
	v_lshl_add_u64 v[254:255], v[96:97], 0, v[250:251]
	s_waitcnt lgkmcnt(0)
	ds_read_b128 v[244:247], v249
	ds_read_b128 v[80:83], v249 offset:1024
	s_waitcnt lgkmcnt(1)
	global_store_dwordx4 v[252:253], v[244:247], off
	s_waitcnt lgkmcnt(0)
	global_store_dwordx4 v[254:255], v[80:83], off offset:256
	s_mov_b64 s[28:29], s[22:23]
	s_nop 0
	v_mov_b32_e32 v82, v99
	v_or_b32_e32 v80, 48, v162
	v_pk_fma_f32 v[72:73], v[72:73], v[82:83], v[136:137] op_sel_hi:[1,0,1]
	v_ashrrev_i32_e32 v81, 31, v80
	v_pk_fma_f32 v[78:79], v[78:79], v[82:83], v[142:143] op_sel_hi:[1,0,1]
	v_pk_fma_f32 v[76:77], v[76:77], v[82:83], v[140:141] op_sel_hi:[1,0,1]
	v_pk_fma_f32 v[74:75], v[74:75], v[82:83], v[138:139] op_sel_hi:[1,0,1]
	v_max_f32_e32 v72, 0, v72
	v_max_f32_e32 v73, 0, v73
	v_lshlrev_b64 v[80:81], 13, v[80:81]
	v_max_f32_e32 v76, 0, v76
	v_max_f32_e32 v77, 0, v77
	v_pk_mul_f32 v[84:85], v[72:73], v[72:73]
	v_max_f32_e32 v72, 0, v78
	v_max_f32_e32 v74, 0, v74
	v_max_f32_e32 v73, 0, v79
	v_max_f32_e32 v75, 0, v75
	v_lshl_add_u64 v[80:81], s[26:27], 0, v[80:81]
	v_pk_mul_f32 v[76:77], v[76:77], v[76:77]
	v_pk_mul_f32 v[78:79], v[72:73], v[72:73]
	v_pk_mul_f32 v[86:87], v[74:75], v[74:75]
	v_pk_fma_f32 v[68:69], v[68:69], v[82:83], v[132:133] op_sel_hi:[1,0,1]
	v_pk_fma_f32 v[64:65], v[64:65], v[82:83], v[128:129] op_sel_hi:[1,0,1]
	v_lshl_add_u64 v[80:81], v[80:81], 0, v[164:165]
	v_cvt_pk_bf16_f32 v72, v76, v77
	v_cvt_pk_bf16_f32 v73, v78, v79
	v_cvt_pk_bf16_f32 v74, v84, v85
	v_cvt_pk_bf16_f32 v75, v86, v87
	v_pk_fma_f32 v[70:71], v[70:71], v[82:83], v[134:135] op_sel_hi:[1,0,1]
	v_max_f32_e32 v68, 0, v68
	v_max_f32_e32 v64, 0, v64
	v_max_f32_e32 v69, 0, v69
	v_max_f32_e32 v65, 0, v65
	ds_write_b128 v248, v[72:75]
	v_lshl_add_u64 v[252:253], v[80:81], 0, v[250:251]
	v_pk_mul_f32 v[68:69], v[68:69], v[68:69]
	v_pk_fma_f32 v[66:67], v[66:67], v[82:83], v[130:131] op_sel_hi:[1,0,1]
	v_pk_mul_f32 v[72:73], v[64:65], v[64:65]
	v_max_f32_e32 v64, 0, v70
	v_max_f32_e32 v65, 0, v71
	v_pk_mul_f32 v[70:71], v[64:65], v[64:65]
	v_cvt_pk_bf16_f32 v64, v68, v69
	ds_read2_b32 v[68:69], v177 offset0:128 offset1:144
	v_max_f32_e32 v66, 0, v66
	v_max_f32_e32 v67, 0, v67
	v_pk_mul_f32 v[74:75], v[66:67], v[66:67]
	v_cvt_pk_bf16_f32 v65, v70, v71
	s_waitcnt lgkmcnt(0)
	v_pk_fma_f32 v[60:61], v[60:61], v[68:69], v[140:141] op_sel_hi:[1,0,1]
	v_pk_fma_f32 v[56:57], v[56:57], v[68:69], v[136:137] op_sel_hi:[1,0,1]
	v_cvt_pk_bf16_f32 v66, v72, v73
	v_cvt_pk_bf16_f32 v67, v74, v75
	v_pk_fma_f32 v[62:63], v[62:63], v[68:69], v[142:143] op_sel_hi:[1,0,1]
	v_pk_fma_f32 v[58:59], v[58:59], v[68:69], v[138:139] op_sel_hi:[1,0,1]
	v_max_f32_e32 v60, 0, v60
	v_max_f32_e32 v56, 0, v56
	v_max_f32_e32 v61, 0, v61
	v_max_f32_e32 v57, 0, v57
	ds_write_b128 v248, v[64:67] offset:1024
	v_lshl_add_u64 v[254:255], v[80:81], 0, v[250:251]
	s_waitcnt lgkmcnt(0)
	ds_read_b128 v[244:247], v249
	ds_read_b128 v[64:67], v249 offset:1024
	s_waitcnt lgkmcnt(1)
	global_store_dwordx4 v[252:253], v[244:247], off
	s_waitcnt lgkmcnt(0)
	global_store_dwordx4 v[254:255], v[64:67], off offset:256
	v_pk_mul_f32 v[60:61], v[60:61], v[60:61]
	v_max_f32_e32 v58, 0, v58
	v_pk_mul_f32 v[66:67], v[56:57], v[56:57]
	v_max_f32_e32 v56, 0, v62
	v_max_f32_e32 v57, 0, v63
	v_max_f32_e32 v59, 0, v59
	v_pk_mul_f32 v[62:63], v[56:57], v[56:57]
	v_pk_mul_f32 v[70:71], v[58:59], v[58:59]
	v_cvt_pk_bf16_f32 v56, v60, v61
	v_add_co_u32_e32 v60, vcc, s17, v160
	v_pk_fma_f32 v[48:49], v[48:49], v[68:69], v[128:129] op_sel_hi:[1,0,1]
	v_cvt_pk_bf16_f32 v57, v62, v63
	v_cvt_pk_bf16_f32 v58, v66, v67
	v_cvt_pk_bf16_f32 v59, v70, v71
	v_addc_co_u32_e32 v61, vcc, 0, v161, vcc
	v_pk_fma_f32 v[54:55], v[54:55], v[68:69], v[134:135] op_sel_hi:[1,0,1]
	v_pk_fma_f32 v[52:53], v[52:53], v[68:69], v[132:133] op_sel_hi:[1,0,1]
	v_pk_fma_f32 v[50:51], v[50:51], v[68:69], v[130:131] op_sel_hi:[1,0,1]
	v_max_f32_e32 v48, 0, v48
	v_max_f32_e32 v49, 0, v49
	ds_write_b128 v248, v[56:59]
	v_lshl_add_u64 v[252:253], v[60:61], 0, v[250:251]
	v_max_f32_e32 v52, 0, v52
	v_max_f32_e32 v53, 0, v53
	v_pk_mul_f32 v[56:57], v[48:49], v[48:49]
	v_max_f32_e32 v48, 0, v54
	v_max_f32_e32 v50, 0, v50
	v_max_f32_e32 v49, 0, v55
	v_max_f32_e32 v51, 0, v51
	s_mov_b64 s[26:27], 0x100000
	v_pk_mul_f32 v[52:53], v[52:53], v[52:53]
	v_pk_mul_f32 v[54:55], v[48:49], v[48:49]
	v_pk_mul_f32 v[58:59], v[50:51], v[50:51]
	v_lshl_add_u64 v[64:65], v[160:161], 0, s[26:27]
	v_cvt_pk_bf16_f32 v48, v52, v53
	v_cvt_pk_bf16_f32 v49, v54, v55
	v_cvt_pk_bf16_f32 v50, v56, v57
	v_cvt_pk_bf16_f32 v51, v58, v59
	ds_write_b128 v248, v[48:51] offset:1024
	v_lshl_add_u64 v[254:255], v[64:65], 0, v[250:251]
	s_waitcnt lgkmcnt(0)
	ds_read_b128 v[244:247], v249
	ds_read_b128 v[48:51], v249 offset:1024
	s_waitcnt lgkmcnt(1)
	global_store_dwordx4 v[252:253], v[244:247], off
	s_waitcnt lgkmcnt(0)
	global_store_dwordx4 v[254:255], v[48:51], off offset:256
	s_mov_b32 s17, 0x120000
	s_mov_b64 s[26:27], 0x120000
	v_mov_b32_e32 v50, v69
	v_pk_fma_f32 v[44:45], v[44:45], v[50:51], v[140:141] op_sel_hi:[1,0,1]
	v_pk_fma_f32 v[40:41], v[40:41], v[50:51], v[136:137] op_sel_hi:[1,0,1]
	v_pk_fma_f32 v[46:47], v[46:47], v[50:51], v[142:143] op_sel_hi:[1,0,1]
	v_pk_fma_f32 v[42:43], v[42:43], v[50:51], v[138:139] op_sel_hi:[1,0,1]
	v_max_f32_e32 v44, 0, v44
	v_max_f32_e32 v40, 0, v40
	v_max_f32_e32 v45, 0, v45
	v_max_f32_e32 v41, 0, v41
	v_pk_mul_f32 v[44:45], v[44:45], v[44:45]
	v_pk_mul_f32 v[52:53], v[40:41], v[40:41]
	v_max_f32_e32 v40, 0, v46
	v_max_f32_e32 v42, 0, v42
	v_max_f32_e32 v41, 0, v47
	v_max_f32_e32 v43, 0, v43
	v_pk_mul_f32 v[46:47], v[40:41], v[40:41]
	v_pk_mul_f32 v[54:55], v[42:43], v[42:43]
	v_cvt_pk_bf16_f32 v40, v44, v45
	v_add_co_u32_e32 v44, vcc, s17, v160
	v_pk_fma_f32 v[36:37], v[36:37], v[50:51], v[132:133] op_sel_hi:[1,0,1]
	v_pk_fma_f32 v[32:33], v[32:33], v[50:51], v[128:129] op_sel_hi:[1,0,1]
	v_cvt_pk_bf16_f32 v41, v46, v47
	v_cvt_pk_bf16_f32 v42, v52, v53
	v_cvt_pk_bf16_f32 v43, v54, v55
	v_addc_co_u32_e32 v45, vcc, 0, v161, vcc
	v_pk_fma_f32 v[38:39], v[38:39], v[50:51], v[134:135] op_sel_hi:[1,0,1]
	v_max_f32_e32 v36, 0, v36
	v_max_f32_e32 v32, 0, v32
	v_max_f32_e32 v37, 0, v37
	v_max_f32_e32 v33, 0, v33
	ds_write_b128 v248, v[40:43]
	v_lshl_add_u64 v[252:253], v[44:45], 0, v[250:251]
	v_pk_mul_f32 v[36:37], v[36:37], v[36:37]
	v_pk_fma_f32 v[34:35], v[34:35], v[50:51], v[130:131] op_sel_hi:[1,0,1]
	v_pk_mul_f32 v[40:41], v[32:33], v[32:33]
	v_max_f32_e32 v32, 0, v38
	v_max_f32_e32 v33, 0, v39
	v_pk_mul_f32 v[38:39], v[32:33], v[32:33]
	v_cvt_pk_bf16_f32 v32, v36, v37
	ds_read2_b32 v[36:37], v177 offset0:160 offset1:176
	v_max_f32_e32 v34, 0, v34
	v_max_f32_e32 v35, 0, v35
	v_pk_mul_f32 v[42:43], v[34:35], v[34:35]
	v_lshl_add_u64 v[48:49], v[160:161], 0, s[26:27]
	s_waitcnt lgkmcnt(0)
	v_pk_fma_f32 v[28:29], v[28:29], v[36:37], v[140:141] op_sel_hi:[1,0,1]
	v_pk_fma_f32 v[24:25], v[24:25], v[36:37], v[136:137] op_sel_hi:[1,0,1]
	v_cvt_pk_bf16_f32 v33, v38, v39
	v_cvt_pk_bf16_f32 v34, v40, v41
	v_cvt_pk_bf16_f32 v35, v42, v43
	v_pk_fma_f32 v[30:31], v[30:31], v[36:37], v[142:143] op_sel_hi:[1,0,1]
	v_pk_fma_f32 v[26:27], v[26:27], v[36:37], v[138:139] op_sel_hi:[1,0,1]
	v_max_f32_e32 v28, 0, v28
	v_max_f32_e32 v24, 0, v24
	v_max_f32_e32 v29, 0, v29
	v_max_f32_e32 v25, 0, v25
	ds_write_b128 v248, v[32:35] offset:1024
	v_lshl_add_u64 v[254:255], v[48:49], 0, v[250:251]
	s_waitcnt lgkmcnt(0)
	ds_read_b128 v[244:247], v249
	ds_read_b128 v[32:35], v249 offset:1024
	s_waitcnt lgkmcnt(1)
	global_store_dwordx4 v[252:253], v[244:247], off
	s_waitcnt lgkmcnt(0)
	global_store_dwordx4 v[254:255], v[32:35], off offset:256
	v_pk_mul_f32 v[28:29], v[28:29], v[28:29]
	v_max_f32_e32 v26, 0, v26
	v_pk_mul_f32 v[34:35], v[24:25], v[24:25]
	v_max_f32_e32 v24, 0, v30
	v_max_f32_e32 v25, 0, v31
	v_max_f32_e32 v27, 0, v27
	s_mov_b32 s17, 0x140000
	v_pk_mul_f32 v[30:31], v[24:25], v[24:25]
	v_pk_mul_f32 v[38:39], v[26:27], v[26:27]
	v_cvt_pk_bf16_f32 v24, v28, v29
	v_add_co_u32_e32 v28, vcc, s17, v160
	v_pk_fma_f32 v[16:17], v[16:17], v[36:37], v[128:129] op_sel_hi:[1,0,1]
	v_cvt_pk_bf16_f32 v25, v30, v31
	v_cvt_pk_bf16_f32 v26, v34, v35
	v_cvt_pk_bf16_f32 v27, v38, v39
	v_addc_co_u32_e32 v29, vcc, 0, v161, vcc
	v_pk_fma_f32 v[22:23], v[22:23], v[36:37], v[134:135] op_sel_hi:[1,0,1]
	v_pk_fma_f32 v[20:21], v[20:21], v[36:37], v[132:133] op_sel_hi:[1,0,1]
	v_pk_fma_f32 v[18:19], v[18:19], v[36:37], v[130:131] op_sel_hi:[1,0,1]
	v_max_f32_e32 v16, 0, v16
	v_max_f32_e32 v17, 0, v17
	ds_write_b128 v248, v[24:27]
	v_lshl_add_u64 v[252:253], v[28:29], 0, v[250:251]
	v_max_f32_e32 v20, 0, v20
	v_max_f32_e32 v21, 0, v21
	v_pk_mul_f32 v[24:25], v[16:17], v[16:17]
	v_max_f32_e32 v16, 0, v22
	v_max_f32_e32 v18, 0, v18
	v_max_f32_e32 v17, 0, v23
	v_max_f32_e32 v19, 0, v19
	s_mov_b64 s[26:27], 0x140000
	v_pk_mul_f32 v[20:21], v[20:21], v[20:21]
	v_pk_mul_f32 v[22:23], v[16:17], v[16:17]
	v_pk_mul_f32 v[26:27], v[18:19], v[18:19]
	v_lshl_add_u64 v[32:33], v[160:161], 0, s[26:27]
	v_cvt_pk_bf16_f32 v16, v20, v21
	v_cvt_pk_bf16_f32 v17, v22, v23
	v_cvt_pk_bf16_f32 v18, v24, v25
	v_cvt_pk_bf16_f32 v19, v26, v27
	ds_write_b128 v248, v[16:19] offset:1024
	v_lshl_add_u64 v[254:255], v[32:33], 0, v[250:251]
	s_waitcnt lgkmcnt(0)
	ds_read_b128 v[244:247], v249
	ds_read_b128 v[16:19], v249 offset:1024
	s_waitcnt lgkmcnt(1)
	global_store_dwordx4 v[252:253], v[244:247], off
	s_waitcnt lgkmcnt(0)
	global_store_dwordx4 v[254:255], v[16:19], off offset:256
	s_mov_b32 s17, 0x160000
	s_mov_b64 s[26:27], 0x160000
	v_mov_b32_e32 v18, v37
	v_pk_fma_f32 v[12:13], v[12:13], v[18:19], v[140:141] op_sel_hi:[1,0,1]
	v_pk_fma_f32 v[8:9], v[8:9], v[18:19], v[136:137] op_sel_hi:[1,0,1]
	v_pk_fma_f32 v[14:15], v[14:15], v[18:19], v[142:143] op_sel_hi:[1,0,1]
	v_pk_fma_f32 v[10:11], v[10:11], v[18:19], v[138:139] op_sel_hi:[1,0,1]
	v_max_f32_e32 v12, 0, v12
	v_max_f32_e32 v8, 0, v8
	v_max_f32_e32 v13, 0, v13
	v_max_f32_e32 v9, 0, v9
	v_pk_mul_f32 v[12:13], v[12:13], v[12:13]
	v_pk_mul_f32 v[20:21], v[8:9], v[8:9]
	v_max_f32_e32 v8, 0, v14
	v_max_f32_e32 v10, 0, v10
	v_max_f32_e32 v9, 0, v15
	v_max_f32_e32 v11, 0, v11
	v_pk_mul_f32 v[14:15], v[8:9], v[8:9]
	v_pk_mul_f32 v[22:23], v[10:11], v[10:11]
	v_cvt_pk_bf16_f32 v8, v12, v13
	v_add_co_u32_e32 v12, vcc, s17, v160
	v_pk_fma_f32 v[0:1], v[0:1], v[18:19], v[128:129] op_sel_hi:[1,0,1]
	v_cvt_pk_bf16_f32 v9, v14, v15
	v_cvt_pk_bf16_f32 v10, v20, v21
	v_cvt_pk_bf16_f32 v11, v22, v23
	v_addc_co_u32_e32 v13, vcc, 0, v161, vcc
	v_pk_fma_f32 v[6:7], v[6:7], v[18:19], v[134:135] op_sel_hi:[1,0,1]
	v_pk_fma_f32 v[4:5], v[4:5], v[18:19], v[132:133] op_sel_hi:[1,0,1]
	v_pk_fma_f32 v[2:3], v[2:3], v[18:19], v[130:131] op_sel_hi:[1,0,1]
	v_max_f32_e32 v0, 0, v0
	v_max_f32_e32 v1, 0, v1
	ds_write_b128 v248, v[8:11]
	v_lshl_add_u64 v[252:253], v[12:13], 0, v[250:251]
	v_max_f32_e32 v4, 0, v4
	v_max_f32_e32 v5, 0, v5
	v_pk_mul_f32 v[8:9], v[0:1], v[0:1]
	v_max_f32_e32 v0, 0, v6
	v_max_f32_e32 v2, 0, v2
	v_max_f32_e32 v1, 0, v7
	v_max_f32_e32 v3, 0, v3
	v_pk_mul_f32 v[4:5], v[4:5], v[4:5]
	v_pk_mul_f32 v[6:7], v[0:1], v[0:1]
	v_pk_mul_f32 v[10:11], v[2:3], v[2:3]
	v_lshl_add_u64 v[16:17], v[160:161], 0, s[26:27]
	v_cvt_pk_bf16_f32 v0, v4, v5
	v_cvt_pk_bf16_f32 v1, v6, v7
	v_cvt_pk_bf16_f32 v2, v8, v9
	v_cvt_pk_bf16_f32 v3, v10, v11
	s_and_b64 vcc, exec, s[4:5]
	s_mov_b64 s[26:27], s[20:21]
	s_mov_b32 s17, s44
	ds_write_b128 v248, v[0:3] offset:1024
	v_lshl_add_u64 v[254:255], v[16:17], 0, v[250:251]
	s_waitcnt lgkmcnt(0)
	ds_read_b128 v[244:247], v249
	ds_read_b128 v[0:3], v249 offset:1024
	s_waitcnt lgkmcnt(1)
	global_store_dwordx4 v[252:253], v[244:247], off
	s_waitcnt lgkmcnt(0)
	global_store_dwordx4 v[254:255], v[0:3], off offset:256
	s_cbranch_vccz .LBB0_777
	s_waitcnt vmcnt(0)
	s_cmpk_gt_u32 s33, 0xff
	s_cbranch_scc1 .LBB0_794
	s_barrier

.LBB0_1426:
	s_or_b64 exec, exec, s[2:3]
	v_mov_b32_e32 v8, v168
	s_waitcnt lgkmcnt(0)
	s_barrier
	v_and_b32_e32 v244, 63, v168
	v_and_b32_e32 v245, 15, v244
	v_lshrrev_b32_e32 v246, 4, v244
	v_lshrrev_b32_e32 v247, 6, v168
	v_bfe_u32 v248, v245, 1, 2
	v_xor_b32_e32 v248, v248, v246
	v_lshlrev_b32_e32 v248, 4, v248
	v_lshl_add_u32 v248, v245, 6, v248
	v_lshl_add_u32 v248, v247, 11, v248
	v_add_u32_e32 v248, 0x22410, v248
	v_bfe_u32 v249, v244, 3, 2
	v_and_b32_e32 v252, 3, v244
	v_xor_b32_e32 v249, v249, v252
	v_lshlrev_b32_e32 v249, 4, v249
	v_lshrrev_b32_e32 v253, 2, v244
	v_lshl_add_u32 v249, v253, 6, v249
	v_lshl_add_u32 v249, v247, 11, v249
	v_add_u32_e32 v249, 0x22410, v249
	v_sub_u32_e32 v250, v253, v245
	v_sub_u32_e32 v251, v252, v246
	v_lshlrev_b32_e32 v251, 4, v251
	v_lshl_add_u32 v250, v250, 13, v251
	v_ashrrev_i32_e32 v251, 31, v250
	s_cmpk_lt_i32 s69, 0x1000
	s_nop 0
	v_readfirstlane_b32 s33, v8
	s_cbranch_scc0 .LBB0_1448
	v_lshlrev_b32_e32 v10, 4, v8
	v_add_u32_e32 v0, 0x2000, v10
	v_ashrrev_i32_e32 v1, 31, v0
	v_lshrrev_b32_e32 v1, 22, v1
	v_add_u32_e32 v1, v0, v1
	v_ashrrev_i32_e32 v9, 10, v1
	v_mul_i32_i24_e32 v1, 0x400, v9
	v_sub_u32_e32 v0, v0, v1
	v_lshrrev_b32_e32 v1, 4, v0
	s_add_u32 s42, s64, 0x1000000
	v_readlane_b32 s2, v242, 18
	v_bitop3_b32 v0, v1, v0, 32 bitop3:0x6c
	s_addc_u32 s43, s65, 0
	v_readlane_b32 s3, v242, 19
	v_ashrrev_i32_e32 v1, 31, v0
	s_movk_i32 s44, 0x201
	s_and_b64 s[2:3], s[2:3], exec
	v_lshrrev_b32_e32 v1, 26, v1
	s_cselect_b32 s2, s44, 0x200
	v_readlane_b32 s3, v242, 20
	v_add_u32_e32 v1, v0, v1
	v_lshlrev_b32_e32 v2, 3, v9
	s_mul_i32 s2, s2, s3
	v_readlane_b32 s3, v242, 17
	v_ashrrev_i32_e32 v11, 6, v1
	v_and_b32_e32 v2, -16, v2
	s_add_i32 s2, s2, s3
	v_add_u32_e32 v2, v11, v2
	s_ashr_i32 s3, s2, 31
	v_and_b32_e32 v3, 3, v11
	s_mov_b32 s12, 0x1fffe0
	v_lshrrev_b32_e32 v4, 2, v2
	v_lshlrev_b32_e32 v5, 1, v2
	v_and_b32_e32 v1, 0xc0, v1
	s_lshr_b32 s3, s3, 25
	v_and_or_b32 v3, v2, s12, v3
	v_and_b32_e32 v4, 4, v4
	v_and_b32_e32 v5, 24, v5
	v_sub_u32_e32 v0, v0, v1
	v_mov_b32_e32 v1, 1
	s_add_i32 s3, s2, s3
	v_or3_b32 v3, v3, v4, v5
	v_lshlrev_b32_e32 v4, 5, v9
	v_ashrrev_i16_sdwa v0, v1, sext(v0) dst_sel:DWORD dst_unused:UNUSED_PAD src0_sel:DWORD src1_sel:BYTE_0
	s_ashr_i32 s4, s3, 7
	s_and_b32 s3, s3, 0xff80
	v_and_b32_e32 v4, 32, v4
	v_bfe_i32 v12, v0, 0, 16
	s_sub_i32 s3, s2, s3
	v_add_lshl_u32 v0, v4, v12, 1
	s_bfe_i32 s2, s3, 0x80000
	v_lshl_add_u32 v144, v3, 11, v0
	v_lshl_add_u32 v146, v2, 11, v0
	v_bfe_i32 v0, v8, 27, 1
	s_bfe_u32 s2, s2, 0x3000c
	v_lshrrev_b32_e32 v0, 22, v0
	s_add_i32 s5, s3, s2
	v_add_u32_e32 v0, v10, v0
	s_bfe_i32 s2, s5, 0x80000
	s_and_b32 s5, s5, 0xf8
	v_ashrrev_i32_e32 v13, 10, v0
	s_sub_i32 s3, s3, s5
	v_mul_i32_i24_e32 v0, 0x400, v13
	s_lshl_b32 s4, s4, 3
	s_sext_i32_i16 s2, s2
	s_sext_i32_i8 s3, s3
	v_sub_u32_e32 v0, v10, v0
	s_lshr_b32 s2, s2, 3
	s_add_i32 s34, s4, s3
	v_lshrrev_b32_e32 v2, 4, v0
	s_ashr_i32 s35, s34, 31
	s_bfe_i64 s[10:11], s[2:3], 0x100000
	v_bitop3_b32 v0, v2, v0, 32 bitop3:0x6c
	s_lshl_b64 s[4:5], s[34:35], 19
	s_lshl_b64 s[10:11], s[10:11], 19
	v_ashrrev_i32_e32 v2, 31, v0
	s_add_u32 s38, s42, s10
	v_lshrrev_b32_e32 v2, 26, v2
	s_addc_u32 s39, s43, s11
	v_add_u32_e32 v2, v0, v2
	v_lshlrev_b32_e32 v3, 3, v13
	s_add_u32 s36, s6, s4
	v_ashrrev_i32_e32 v14, 6, v2
	v_and_b32_e32 v3, -16, v3
	s_addc_u32 s37, s7, s5
	s_ashr_i32 s35, s33, 6
	v_add_u32_e32 v3, v14, v3
	s_ashr_i32 s3, s33, 8
	s_lshl_b32 s45, s35, 10
	v_and_b32_e32 v4, 3, v14
	v_lshrrev_b32_e32 v5, 2, v3
	v_lshlrev_b32_e32 v6, 1, v3
	v_and_b32_e32 v2, 0xc0, v2
	s_add_u32 s4, s36, 0x40000
	v_and_or_b32 v4, v3, s12, v4
	v_and_b32_e32 v5, 4, v5
	v_and_b32_e32 v6, 24, v6
	v_sub_u32_e32 v0, v0, v2
	s_addc_u32 s5, s37, 0
	v_or3_b32 v4, v4, v5, v6
	v_lshlrev_b32_e32 v5, 5, v13
	v_ashrrev_i16_sdwa v0, v1, sext(v0) dst_sel:DWORD dst_unused:UNUSED_PAD src0_sel:DWORD src1_sel:BYTE_0
	s_add_u32 s10, s38, 0x40000
	v_and_b32_e32 v5, 32, v5
	v_bfe_i32 v15, v0, 0, 16
	s_addc_u32 s11, s39, 0
	v_add_lshl_u32 v0, v5, v15, 1
	s_add_i32 s46, s45, 0
	v_lshl_add_u32 v148, v4, 11, v0
	s_add_i32 m0, s46, 0x10000
	v_lshl_add_u32 v150, v3, 11, v0
	global_load_lds_dwordx4 v148, s[38:39]
	s_add_i32 m0, s46, 0x12000
	s_add_i32 s47, s46, 0x2000
	global_load_lds_dwordx4 v144, s[38:39]
	s_mov_b32 m0, s46
	s_add_i32 s48, s46, 0x4000
	global_load_lds_dwordx4 v150, s[36:37]
	s_mov_b32 m0, s47
	s_add_i32 s49, s46, 0x6000
	global_load_lds_dwordx4 v146, s[36:37]
	s_add_i32 m0, s46, 0x14000
	v_mov_b32_e32 v149, 0
	global_load_lds_dwordx4 v148, s[10:11]
	s_add_i32 m0, s46, 0x16000
	v_mov_b32_e32 v145, v149
	global_load_lds_dwordx4 v144, s[10:11]
	s_mov_b32 m0, s48
	v_mov_b32_e32 v151, v149
	global_load_lds_dwordx4 v150, s[4:5]
	s_mov_b32 m0, s49
	v_mov_b32_e32 v147, v149
	global_load_lds_dwordx4 v146, s[4:5]
	s_mov_b32 s25, 0
	v_lshl_add_u64 v[6:7], s[38:39], 0, v[148:149]
	v_lshl_add_u64 v[4:5], s[38:39], 0, v[144:145]
	v_lshl_add_u64 v[2:3], s[36:37], 0, v[150:151]
	s_cmp_lg_u32 s3, 1
	v_lshl_add_u64 v[0:1], s[36:37], 0, v[146:147]
	s_cbranch_scc1 .LBB0_1429
	s_barrier

.LBB0_1443:
	ds_read_b128 v[128:131], v173
	ds_read_b128 v[132:135], v173 offset:1024
	ds_read_b128 v[136:139], v173 offset:2048
	ds_read_b128 v[140:143], v173 offset:3072
	s_add_u32 s38, s36, 0xfffc0080
	s_addc_u32 s39, s37, -1
	s_cmp_eq_u32 s65, 12
	s_cselect_b32 s41, s27, s39
	s_cselect_b32 s40, s61, s38
	s_cselect_b32 s39, s25, s64
	s_cselect_b32 s38, s62, s63
	v_lshl_add_u64 v[164:165], s[36:37], 0, v[152:153]
	s_add_i32 m0, s46, 0xc000
	ds_read_b128 v[160:163], v174
	ds_read_b128 v[176:179], v174 offset:1024
	ds_read_b128 v[180:183], v174 offset:2048
	ds_read_b128 v[184:187], v174 offset:3072
	ds_read_b128 v[188:191], v174 offset:4096
	ds_read_b128 v[192:195], v174 offset:5120
	ds_read_b128 v[196:199], v174 offset:6144
	ds_read_b128 v[200:203], v174 offset:7168
	global_load_lds_dwordx4 v[164:165], off
	v_lshl_add_u64 v[164:165], s[36:37], 0, v[154:155]
	s_add_i32 m0, s46, 0xe000
	s_nop 0
	global_load_lds_dwordx4 v[164:165], off
	s_waitcnt lgkmcnt(8)
	s_barrier
	s_waitcnt lgkmcnt(0)
	s_setprio 1
	s_waitcnt lgkmcnt(0)
	v_mfma_f32_16x16x32_bf16 v[124:127], v[128:131], v[160:163], v[124:127]
	v_mfma_f32_16x16x32_bf16 v[120:123], v[136:139], v[160:163], v[120:123]
	v_mfma_f32_16x16x32_bf16 v[108:111], v[128:131], v[180:183], v[108:111]
	v_mfma_f32_16x16x32_bf16 v[104:107], v[136:139], v[180:183], v[104:107]
	v_mfma_f32_16x16x32_bf16 v[92:95], v[128:131], v[188:191], v[92:95]
	v_mfma_f32_16x16x32_bf16 v[88:91], v[136:139], v[188:191], v[88:91]
	v_mfma_f32_16x16x32_bf16 v[76:79], v[128:131], v[196:199], v[76:79]
	v_mfma_f32_16x16x32_bf16 v[72:75], v[136:139], v[196:199], v[72:75]
	v_mfma_f32_16x16x32_bf16 v[124:127], v[132:135], v[176:179], v[124:127]
	v_mfma_f32_16x16x32_bf16 v[120:123], v[140:143], v[176:179], v[120:123]
	v_mfma_f32_16x16x32_bf16 v[108:111], v[132:135], v[184:187], v[108:111]
	v_mfma_f32_16x16x32_bf16 v[104:107], v[140:143], v[184:187], v[104:107]
	v_mfma_f32_16x16x32_bf16 v[92:95], v[132:135], v[192:195], v[92:95]
	v_mfma_f32_16x16x32_bf16 v[88:91], v[140:143], v[192:195], v[88:91]
	v_mfma_f32_16x16x32_bf16 v[76:79], v[132:135], v[200:203], v[76:79]
	v_mfma_f32_16x16x32_bf16 v[72:75], v[140:143], v[200:203], v[72:75]
	s_setprio 0
	s_barrier
	s_add_i32 s66, s52, s45
	v_lshl_add_u64 v[164:165], s[38:39], 0, v[148:149]
	s_mov_b32 m0, s66
	ds_read_b128 v[204:207], v175
	ds_read_b128 v[208:211], v175 offset:1024
	ds_read_b128 v[212:215], v175 offset:2048
	ds_read_b128 v[216:219], v175 offset:3072
	global_load_lds_dwordx4 v[164:165], off
	v_lshl_add_u64 v[220:221], s[38:39], 0, v[144:145]
	s_add_i32 m0, s66, 0x2000
	s_nop 0
	global_load_lds_dwordx4 v[220:221], off
	s_barrier
	s_waitcnt lgkmcnt(0)
	s_setprio 1
	s_waitcnt lgkmcnt(0)
	v_mfma_f32_16x16x32_bf16 v[116:119], v[204:207], v[160:163], v[116:119]
	v_mfma_f32_16x16x32_bf16 v[112:115], v[212:215], v[160:163], v[112:115]
	v_mfma_f32_16x16x32_bf16 v[100:103], v[204:207], v[180:183], v[100:103]
	v_mfma_f32_16x16x32_bf16 v[96:99], v[212:215], v[180:183], v[96:99]
	v_mfma_f32_16x16x32_bf16 v[84:87], v[204:207], v[188:191], v[84:87]
	v_mfma_f32_16x16x32_bf16 v[80:83], v[212:215], v[188:191], v[80:83]
	v_mfma_f32_16x16x32_bf16 v[68:71], v[204:207], v[196:199], v[68:71]
	v_mfma_f32_16x16x32_bf16 v[64:67], v[212:215], v[196:199], v[64:67]
	v_mfma_f32_16x16x32_bf16 v[116:119], v[208:211], v[176:179], v[116:119]
	v_mfma_f32_16x16x32_bf16 v[112:115], v[216:219], v[176:179], v[112:115]
	v_mfma_f32_16x16x32_bf16 v[100:103], v[208:211], v[184:187], v[100:103]
	v_mfma_f32_16x16x32_bf16 v[96:99], v[216:219], v[184:187], v[96:99]
	v_mfma_f32_16x16x32_bf16 v[84:87], v[208:211], v[192:195], v[84:87]
	v_mfma_f32_16x16x32_bf16 v[80:83], v[216:219], v[192:195], v[80:83]
	v_mfma_f32_16x16x32_bf16 v[68:71], v[208:211], v[200:203], v[68:71]
	v_mfma_f32_16x16x32_bf16 v[64:67], v[216:219], v[200:203], v[64:67]
	s_setprio 0
	s_mov_b32 m0, s46
	v_lshl_add_u64 v[222:223], s[40:41], 0, v[150:151]
	s_barrier
	ds_read_b128 v[160:163], v174 offset:16384
	ds_read_b128 v[176:179], v174 offset:17408
	ds_read_b128 v[180:183], v174 offset:18432
	ds_read_b128 v[184:187], v174 offset:19456
	ds_read_b128 v[188:191], v174 offset:20480
	ds_read_b128 v[192:195], v174 offset:21504
	ds_read_b128 v[196:199], v174 offset:22528
	ds_read_b128 v[200:203], v174 offset:23552
	global_load_lds_dwordx4 v[222:223], off
	v_lshl_add_u64 v[224:225], s[40:41], 0, v[146:147]
	s_mov_b32 m0, s47
	s_nop 0
	global_load_lds_dwordx4 v[224:225], off
	s_barrier
	s_waitcnt lgkmcnt(0)
	s_setprio 1
	s_waitcnt lgkmcnt(0)
	v_mfma_f32_16x16x32_bf16 v[60:63], v[128:131], v[160:163], v[60:63]
	v_mfma_f32_16x16x32_bf16 v[56:59], v[136:139], v[160:163], v[56:59]
	v_mfma_f32_16x16x32_bf16 v[44:47], v[128:131], v[180:183], v[44:47]
	v_mfma_f32_16x16x32_bf16 v[40:43], v[136:139], v[180:183], v[40:43]
	v_mfma_f32_16x16x32_bf16 v[28:31], v[128:131], v[188:191], v[28:31]
	v_mfma_f32_16x16x32_bf16 v[24:27], v[136:139], v[188:191], v[24:27]
	v_mfma_f32_16x16x32_bf16 v[12:15], v[128:131], v[196:199], v[12:15]
	v_mfma_f32_16x16x32_bf16 v[8:11], v[136:139], v[196:199], v[8:11]
	v_mfma_f32_16x16x32_bf16 v[60:63], v[132:135], v[176:179], v[60:63]
	v_mfma_f32_16x16x32_bf16 v[56:59], v[140:143], v[176:179], v[56:59]
	v_mfma_f32_16x16x32_bf16 v[44:47], v[132:135], v[184:187], v[44:47]
	v_mfma_f32_16x16x32_bf16 v[40:43], v[140:143], v[184:187], v[40:43]
	v_mfma_f32_16x16x32_bf16 v[28:31], v[132:135], v[192:195], v[28:31]
	v_mfma_f32_16x16x32_bf16 v[24:27], v[140:143], v[192:195], v[24:27]
	v_mfma_f32_16x16x32_bf16 v[12:15], v[132:135], v[200:203], v[12:15]
	v_mfma_f32_16x16x32_bf16 v[8:11], v[140:143], v[200:203], v[8:11]
	s_setprio 0
	s_barrier
	s_add_u32 s66, s38, 0x40000
	s_addc_u32 s67, s39, 0
	s_add_i32 s68, s53, s45
	v_lshl_add_u64 v[128:129], s[66:67], 0, v[148:149]
	s_mov_b32 m0, s68
	s_nop 0
	global_load_lds_dwordx4 v[128:129], off
	v_lshl_add_u64 v[128:129], s[66:67], 0, v[144:145]
	s_add_i32 m0, s68, 0x2000
	s_nop 0
	global_load_lds_dwordx4 v[128:129], off
	s_waitcnt vmcnt(6)
	s_barrier
	s_setprio 1
	v_mfma_f32_16x16x32_bf16 v[52:55], v[204:207], v[160:163], v[52:55]
	v_mfma_f32_16x16x32_bf16 v[48:51], v[212:215], v[160:163], v[48:51]
	v_mfma_f32_16x16x32_bf16 v[36:39], v[204:207], v[180:183], v[36:39]
	v_mfma_f32_16x16x32_bf16 v[32:35], v[212:215], v[180:183], v[32:35]
	v_mfma_f32_16x16x32_bf16 v[20:23], v[204:207], v[188:191], v[20:23]
	v_mfma_f32_16x16x32_bf16 v[16:19], v[212:215], v[188:191], v[16:19]
	v_mfma_f32_16x16x32_bf16 v[4:7], v[204:207], v[196:199], v[4:7]
	v_mfma_f32_16x16x32_bf16 v[0:3], v[212:215], v[196:199], v[0:3]
	v_mfma_f32_16x16x32_bf16 v[52:55], v[208:211], v[176:179], v[52:55]
	v_mfma_f32_16x16x32_bf16 v[48:51], v[216:219], v[176:179], v[48:51]
	v_mfma_f32_16x16x32_bf16 v[36:39], v[208:211], v[184:187], v[36:39]
	v_mfma_f32_16x16x32_bf16 v[32:35], v[216:219], v[184:187], v[32:35]
	v_mfma_f32_16x16x32_bf16 v[20:23], v[208:211], v[192:195], v[20:23]
	v_mfma_f32_16x16x32_bf16 v[16:19], v[216:219], v[192:195], v[16:19]
	v_mfma_f32_16x16x32_bf16 v[4:7], v[208:211], v[200:203], v[4:7]
	v_mfma_f32_16x16x32_bf16 v[0:3], v[216:219], v[200:203], v[0:3]
	s_setprio 0
	s_add_i32 s66, 0, 0x18000
	v_add_u32_e32 v140, s66, v169
	s_barrier
	ds_read_b128 v[128:131], v140
	ds_read_b128 v[132:135], v140 offset:1024
	ds_read_b128 v[136:139], v140 offset:2048
	ds_read_b128 v[140:143], v140 offset:3072
	s_add_u32 s40, s40, 0x40000
	s_addc_u32 s41, s41, 0
	s_mov_b32 m0, s48
	v_lshl_add_u64 v[204:205], s[40:41], 0, v[150:151]
	ds_read_b128 v[160:163], v174 offset:32768
	ds_read_b128 v[176:179], v174 offset:33792
	ds_read_b128 v[180:183], v174 offset:34816
	ds_read_b128 v[184:187], v174 offset:35840
	ds_read_b128 v[188:191], v174 offset:36864
	ds_read_b128 v[192:195], v174 offset:37888
	ds_read_b128 v[196:199], v174 offset:38912
	ds_read_b128 v[200:203], v174 offset:39936
	global_load_lds_dwordx4 v[204:205], off
	v_lshl_add_u64 v[204:205], s[40:41], 0, v[146:147]
	s_mov_b32 m0, s49
	s_nop 0
	global_load_lds_dwordx4 v[204:205], off
	s_waitcnt lgkmcnt(8)
	s_barrier
	s_waitcnt lgkmcnt(0)
	s_setprio 1
	s_waitcnt lgkmcnt(0)
	v_mfma_f32_16x16x32_bf16 v[124:127], v[128:131], v[160:163], v[124:127]
	v_mfma_f32_16x16x32_bf16 v[120:123], v[136:139], v[160:163], v[120:123]
	v_mfma_f32_16x16x32_bf16 v[108:111], v[128:131], v[180:183], v[108:111]
	v_mfma_f32_16x16x32_bf16 v[104:107], v[136:139], v[180:183], v[104:107]
	v_mfma_f32_16x16x32_bf16 v[92:95], v[128:131], v[188:191], v[92:95]
	v_mfma_f32_16x16x32_bf16 v[88:91], v[136:139], v[188:191], v[88:91]
	v_mfma_f32_16x16x32_bf16 v[76:79], v[128:131], v[196:199], v[76:79]
	v_mfma_f32_16x16x32_bf16 v[72:75], v[136:139], v[196:199], v[72:75]
	v_mfma_f32_16x16x32_bf16 v[124:127], v[132:135], v[176:179], v[124:127]
	v_mfma_f32_16x16x32_bf16 v[120:123], v[140:143], v[176:179], v[120:123]
	v_mfma_f32_16x16x32_bf16 v[108:111], v[132:135], v[184:187], v[108:111]
	v_mfma_f32_16x16x32_bf16 v[104:107], v[140:143], v[184:187], v[104:107]
	v_mfma_f32_16x16x32_bf16 v[92:95], v[132:135], v[192:195], v[92:95]
	v_mfma_f32_16x16x32_bf16 v[88:91], v[140:143], v[192:195], v[88:91]
	v_mfma_f32_16x16x32_bf16 v[76:79], v[132:135], v[200:203], v[76:79]
	v_mfma_f32_16x16x32_bf16 v[72:75], v[140:143], v[200:203], v[72:75]
	s_setprio 0
	s_barrier
	s_add_i32 s40, 0, 0x1c000
	s_add_i32 s41, s66, s45
	v_add_u32_e32 v216, s40, v169
	v_lshl_add_u64 v[164:165], v[164:165], 0, s[10:11]
	s_mov_b32 m0, s41
	ds_read_b128 v[204:207], v216
	ds_read_b128 v[208:211], v216 offset:1024
	ds_read_b128 v[212:215], v216 offset:2048
	ds_read_b128 v[216:219], v216 offset:3072
	global_load_lds_dwordx4 v[164:165], off
	v_lshl_add_u64 v[164:165], v[220:221], 0, s[10:11]
	s_add_i32 m0, s41, 0x2000
	s_nop 0
	global_load_lds_dwordx4 v[164:165], off
	s_barrier
	s_waitcnt lgkmcnt(0)
	s_setprio 1
	s_waitcnt lgkmcnt(0)
	v_mfma_f32_16x16x32_bf16 v[116:119], v[204:207], v[160:163], v[116:119]
	v_mfma_f32_16x16x32_bf16 v[112:115], v[212:215], v[160:163], v[112:115]
	v_mfma_f32_16x16x32_bf16 v[100:103], v[204:207], v[180:183], v[100:103]
	v_mfma_f32_16x16x32_bf16 v[96:99], v[212:215], v[180:183], v[96:99]
	v_mfma_f32_16x16x32_bf16 v[84:87], v[204:207], v[188:191], v[84:87]
	v_mfma_f32_16x16x32_bf16 v[80:83], v[212:215], v[188:191], v[80:83]
	v_mfma_f32_16x16x32_bf16 v[68:71], v[204:207], v[196:199], v[68:71]
	v_mfma_f32_16x16x32_bf16 v[64:67], v[212:215], v[196:199], v[64:67]
	v_mfma_f32_16x16x32_bf16 v[116:119], v[208:211], v[176:179], v[116:119]
	v_mfma_f32_16x16x32_bf16 v[112:115], v[216:219], v[176:179], v[112:115]
	v_mfma_f32_16x16x32_bf16 v[100:103], v[208:211], v[184:187], v[100:103]
	v_mfma_f32_16x16x32_bf16 v[96:99], v[216:219], v[184:187], v[96:99]
	v_mfma_f32_16x16x32_bf16 v[84:87], v[208:211], v[192:195], v[84:87]
	v_mfma_f32_16x16x32_bf16 v[80:83], v[216:219], v[192:195], v[80:83]
	v_mfma_f32_16x16x32_bf16 v[68:71], v[208:211], v[200:203], v[68:71]
	v_mfma_f32_16x16x32_bf16 v[64:67], v[216:219], v[200:203], v[64:67]
	s_setprio 0
	s_mov_b32 m0, s50
	v_lshl_add_u64 v[164:165], v[222:223], 0, s[10:11]
	s_barrier
	ds_read_b128 v[160:163], v174 offset:49152
	ds_read_b128 v[176:179], v174 offset:50176
	ds_read_b128 v[180:183], v174 offset:51200
	ds_read_b128 v[184:187], v174 offset:52224
	ds_read_b128 v[188:191], v174 offset:53248
	ds_read_b128 v[192:195], v174 offset:54272
	ds_read_b128 v[196:199], v174 offset:55296
	ds_read_b128 v[200:203], v174 offset:56320
	global_load_lds_dwordx4 v[164:165], off
	v_lshl_add_u64 v[164:165], v[224:225], 0, s[10:11]
	s_mov_b32 m0, s51
	s_nop 0
	global_load_lds_dwordx4 v[164:165], off
	s_barrier
	s_waitcnt lgkmcnt(0)
	s_setprio 1
	s_waitcnt lgkmcnt(0)
	v_mfma_f32_16x16x32_bf16 v[60:63], v[128:131], v[160:163], v[60:63]
	v_mfma_f32_16x16x32_bf16 v[56:59], v[136:139], v[160:163], v[56:59]
	v_mfma_f32_16x16x32_bf16 v[44:47], v[128:131], v[180:183], v[44:47]
	v_mfma_f32_16x16x32_bf16 v[40:43], v[136:139], v[180:183], v[40:43]
	v_mfma_f32_16x16x32_bf16 v[28:31], v[128:131], v[188:191], v[28:31]
	v_mfma_f32_16x16x32_bf16 v[24:27], v[136:139], v[188:191], v[24:27]
	v_mfma_f32_16x16x32_bf16 v[12:15], v[128:131], v[196:199], v[12:15]
	v_mfma_f32_16x16x32_bf16 v[8:11], v[136:139], v[196:199], v[8:11]
	v_mfma_f32_16x16x32_bf16 v[60:63], v[132:135], v[176:179], v[60:63]
	v_mfma_f32_16x16x32_bf16 v[56:59], v[140:143], v[176:179], v[56:59]
	v_mfma_f32_16x16x32_bf16 v[44:47], v[132:135], v[184:187], v[44:47]
	v_mfma_f32_16x16x32_bf16 v[40:43], v[140:143], v[184:187], v[40:43]
	v_mfma_f32_16x16x32_bf16 v[28:31], v[132:135], v[192:195], v[28:31]
	v_mfma_f32_16x16x32_bf16 v[24:27], v[140:143], v[192:195], v[24:27]
	v_mfma_f32_16x16x32_bf16 v[12:15], v[132:135], v[200:203], v[12:15]
	v_mfma_f32_16x16x32_bf16 v[8:11], v[140:143], v[200:203], v[8:11]
	s_setprio 0
	s_barrier
	s_add_u32 s38, s38, 0x40080
	s_addc_u32 s39, s39, 0
	s_add_i32 s40, s40, s45
	v_lshl_add_u64 v[128:129], s[38:39], 0, v[148:149]
	s_mov_b32 m0, s40
	s_nop 0
	global_load_lds_dwordx4 v[128:129], off
	v_lshl_add_u64 v[128:129], s[38:39], 0, v[144:145]
	s_add_i32 m0, s40, 0x2000
	s_nop 0
	global_load_lds_dwordx4 v[128:129], off
	s_waitcnt vmcnt(6)
	s_barrier
	s_setprio 1
	v_mfma_f32_16x16x32_bf16 v[52:55], v[204:207], v[160:163], v[52:55]
	v_mfma_f32_16x16x32_bf16 v[48:51], v[212:215], v[160:163], v[48:51]
	v_mfma_f32_16x16x32_bf16 v[36:39], v[204:207], v[180:183], v[36:39]
	v_mfma_f32_16x16x32_bf16 v[32:35], v[212:215], v[180:183], v[32:35]
	v_mfma_f32_16x16x32_bf16 v[20:23], v[204:207], v[188:191], v[20:23]
	v_mfma_f32_16x16x32_bf16 v[16:19], v[212:215], v[188:191], v[16:19]
	v_mfma_f32_16x16x32_bf16 v[4:7], v[204:207], v[196:199], v[4:7]
	v_mfma_f32_16x16x32_bf16 v[0:3], v[212:215], v[196:199], v[0:3]
	v_mfma_f32_16x16x32_bf16 v[52:55], v[208:211], v[176:179], v[52:55]
	v_mfma_f32_16x16x32_bf16 v[48:51], v[216:219], v[176:179], v[48:51]
	v_mfma_f32_16x16x32_bf16 v[36:39], v[208:211], v[184:187], v[36:39]
	v_mfma_f32_16x16x32_bf16 v[32:35], v[216:219], v[184:187], v[32:35]
	v_mfma_f32_16x16x32_bf16 v[20:23], v[208:211], v[192:195], v[20:23]
	v_mfma_f32_16x16x32_bf16 v[16:19], v[216:219], v[192:195], v[16:19]
	v_mfma_f32_16x16x32_bf16 v[4:7], v[208:211], v[200:203], v[4:7]
	v_mfma_f32_16x16x32_bf16 v[0:3], v[216:219], v[200:203], v[0:3]
	s_setprio 0
	s_add_i32 s65, s65, 2
	s_add_u32 s36, s36, 0x100
	s_addc_u32 s37, s37, 0
	s_add_u32 s63, s63, 0x100
	s_addc_u32 s64, s64, 0
	s_cmp_gt_u32 s65, 13
	s_barrier
	s_cbranch_scc0 .LBB0_1443
	v_add_u32_e32 v164, s60, v167
	v_add_u32_e32 v128, s60, v172
	v_add_u32_e32 v176, 0x400, v164
	ds_read_b128 v[140:143], v128
	ds_read_b128 v[136:139], v128 offset:16
	ds_read_b128 v[132:135], v128 offset:512
	ds_read_b128 v[128:131], v128 offset:528
	ds_read2_b32 v[178:179], v176 offset1:16
	v_lshl_add_u32 v162, s34, 8, v166
	v_lshl_or_b32 v160, s59, 8, v171
	v_ashrrev_i32_e32 v163, 31, v162
	v_readlane_b32 s36, v243, 56
	v_ashrrev_i32_e32 v161, 31, v160
	v_lshlrev_b64 v[164:165], 13, v[162:163]
	v_readlane_b32 s37, v243, 57
	s_waitcnt lgkmcnt(0)
	v_pk_fma_f32 v[120:121], v[120:121], v[178:179], v[136:137] op_sel_hi:[1,0,1]
	v_pk_fma_f32 v[126:127], v[126:127], v[178:179], v[142:143] op_sel_hi:[1,0,1]
	v_lshl_add_u64 v[180:181], s[36:37], 0, v[164:165]
	v_lshlrev_b64 v[164:165], 1, v[160:161]
	v_pk_fma_f32 v[124:125], v[124:125], v[178:179], v[140:141] op_sel_hi:[1,0,1]
	v_pk_fma_f32 v[122:123], v[122:123], v[178:179], v[138:139] op_sel_hi:[1,0,1]
	v_max_f32_e32 v120, 0, v120
	v_max_f32_e32 v121, 0, v121
	v_lshl_add_u64 v[160:161], v[180:181], 0, v[164:165]
	v_max_f32_e32 v124, 0, v124
	v_max_f32_e32 v125, 0, v125
	v_pk_mul_f32 v[180:181], v[120:121], v[120:121]
	v_max_f32_e32 v120, 0, v126
	v_max_f32_e32 v122, 0, v122
	v_max_f32_e32 v121, 0, v127
	v_max_f32_e32 v123, 0, v123
	v_pk_mul_f32 v[124:125], v[124:125], v[124:125]
	v_pk_mul_f32 v[126:127], v[120:121], v[120:121]
	v_pk_mul_f32 v[182:183], v[122:123], v[122:123]
	v_pk_fma_f32 v[112:113], v[112:113], v[178:179], v[128:129] op_sel_hi:[1,0,1]
	v_cvt_pk_bf16_f32 v120, v124, v125
	v_cvt_pk_bf16_f32 v121, v126, v127
	v_cvt_pk_bf16_f32 v122, v180, v181
	v_cvt_pk_bf16_f32 v123, v182, v183
	v_pk_fma_f32 v[118:119], v[118:119], v[178:179], v[134:135] op_sel_hi:[1,0,1]
	v_pk_fma_f32 v[116:117], v[116:117], v[178:179], v[132:133] op_sel_hi:[1,0,1]
	v_pk_fma_f32 v[114:115], v[114:115], v[178:179], v[130:131] op_sel_hi:[1,0,1]
	v_max_f32_e32 v112, 0, v112
	v_max_f32_e32 v113, 0, v113
	ds_write_b128 v248, v[120:123]
	v_lshl_add_u64 v[252:253], v[160:161], 0, v[250:251]
	v_max_f32_e32 v116, 0, v116
	v_max_f32_e32 v117, 0, v117
	v_pk_mul_f32 v[120:121], v[112:113], v[112:113]
	v_max_f32_e32 v112, 0, v118
	v_max_f32_e32 v114, 0, v114
	v_max_f32_e32 v113, 0, v119
	v_max_f32_e32 v115, 0, v115
	v_pk_mul_f32 v[116:117], v[116:117], v[116:117]
	v_pk_mul_f32 v[118:119], v[112:113], v[112:113]
	v_pk_mul_f32 v[122:123], v[114:115], v[114:115]
	v_cvt_pk_bf16_f32 v112, v116, v117
	v_cvt_pk_bf16_f32 v113, v118, v119
	v_cvt_pk_bf16_f32 v114, v120, v121
	v_cvt_pk_bf16_f32 v115, v122, v123
	ds_write_b128 v248, v[112:115] offset:1024
	v_lshl_add_u64 v[254:255], v[160:161], 0, v[250:251]
	s_waitcnt lgkmcnt(0)
	ds_read_b128 v[244:247], v249
	ds_read_b128 v[112:115], v249 offset:1024
	s_waitcnt lgkmcnt(1)
	global_store_dwordx4 v[252:253], v[244:247], off
	s_waitcnt lgkmcnt(0)
	global_store_dwordx4 v[254:255], v[112:115], off offset:256
	v_readlane_b32 s64, v243, 1
	s_mov_b32 s59, s24
	v_mov_b32_e32 v114, v179
	v_or_b32_e32 v112, 16, v162
	v_pk_fma_f32 v[104:105], v[104:105], v[114:115], v[136:137] op_sel_hi:[1,0,1]
	v_ashrrev_i32_e32 v113, 31, v112
	v_pk_fma_f32 v[110:111], v[110:111], v[114:115], v[142:143] op_sel_hi:[1,0,1]
	v_pk_fma_f32 v[108:109], v[108:109], v[114:115], v[140:141] op_sel_hi:[1,0,1]
	v_pk_fma_f32 v[106:107], v[106:107], v[114:115], v[138:139] op_sel_hi:[1,0,1]
	v_max_f32_e32 v104, 0, v104
	v_max_f32_e32 v105, 0, v105
	v_lshlrev_b64 v[112:113], 13, v[112:113]
	v_max_f32_e32 v108, 0, v108
	v_max_f32_e32 v109, 0, v109
	v_pk_mul_f32 v[116:117], v[104:105], v[104:105]
	v_max_f32_e32 v104, 0, v110
	v_max_f32_e32 v106, 0, v106
	v_max_f32_e32 v105, 0, v111
	v_max_f32_e32 v107, 0, v107
	v_lshl_add_u64 v[112:113], s[36:37], 0, v[112:113]
	v_pk_mul_f32 v[108:109], v[108:109], v[108:109]
	v_pk_mul_f32 v[110:111], v[104:105], v[104:105]
	v_pk_mul_f32 v[118:119], v[106:107], v[106:107]
	v_pk_fma_f32 v[96:97], v[96:97], v[114:115], v[128:129] op_sel_hi:[1,0,1]
	v_lshl_add_u64 v[112:113], v[112:113], 0, v[164:165]
	v_cvt_pk_bf16_f32 v104, v108, v109
	v_cvt_pk_bf16_f32 v105, v110, v111
	v_cvt_pk_bf16_f32 v106, v116, v117
	v_cvt_pk_bf16_f32 v107, v118, v119
	v_pk_fma_f32 v[102:103], v[102:103], v[114:115], v[134:135] op_sel_hi:[1,0,1]
	v_pk_fma_f32 v[100:101], v[100:101], v[114:115], v[132:133] op_sel_hi:[1,0,1]
	v_pk_fma_f32 v[98:99], v[98:99], v[114:115], v[130:131] op_sel_hi:[1,0,1]
	v_max_f32_e32 v96, 0, v96
	v_max_f32_e32 v97, 0, v97
	ds_write_b128 v248, v[104:107]
	v_lshl_add_u64 v[252:253], v[112:113], 0, v[250:251]
	v_max_f32_e32 v100, 0, v100
	v_max_f32_e32 v101, 0, v101
	v_pk_mul_f32 v[104:105], v[96:97], v[96:97]
	v_max_f32_e32 v96, 0, v102
	v_max_f32_e32 v98, 0, v98
	v_max_f32_e32 v97, 0, v103
	v_max_f32_e32 v99, 0, v99
	v_pk_mul_f32 v[100:101], v[100:101], v[100:101]
	v_pk_mul_f32 v[102:103], v[96:97], v[96:97]
	v_pk_mul_f32 v[106:107], v[98:99], v[98:99]
	v_cvt_pk_bf16_f32 v96, v100, v101
	v_cvt_pk_bf16_f32 v97, v102, v103
	v_cvt_pk_bf16_f32 v98, v104, v105
	v_cvt_pk_bf16_f32 v99, v106, v107
	ds_write_b128 v248, v[96:99] offset:1024
	v_lshl_add_u64 v[254:255], v[112:113], 0, v[250:251]
	s_waitcnt lgkmcnt(0)
	ds_read_b128 v[244:247], v249
	ds_read_b128 v[96:99], v249 offset:1024
	s_waitcnt lgkmcnt(1)
	global_store_dwordx4 v[252:253], v[244:247], off
	s_waitcnt lgkmcnt(0)
	global_store_dwordx4 v[254:255], v[96:99], off offset:256
	ds_read2_b32 v[98:99], v176 offset0:32 offset1:48
	s_mov_b32 s34, s26
	v_or_b32_e32 v96, 32, v162
	v_ashrrev_i32_e32 v97, 31, v96
	v_lshlrev_b64 v[96:97], 13, v[96:97]
	s_waitcnt lgkmcnt(0)
	v_pk_fma_f32 v[88:89], v[88:89], v[98:99], v[136:137] op_sel_hi:[1,0,1]
	v_pk_fma_f32 v[94:95], v[94:95], v[98:99], v[142:143] op_sel_hi:[1,0,1]
	v_pk_fma_f32 v[92:93], v[92:93], v[98:99], v[140:141] op_sel_hi:[1,0,1]
	v_pk_fma_f32 v[90:91], v[90:91], v[98:99], v[138:139] op_sel_hi:[1,0,1]
	v_max_f32_e32 v88, 0, v88
	v_max_f32_e32 v89, 0, v89
	v_max_f32_e32 v92, 0, v92
	v_max_f32_e32 v93, 0, v93
	v_pk_mul_f32 v[100:101], v[88:89], v[88:89]
	v_max_f32_e32 v88, 0, v94
	v_max_f32_e32 v90, 0, v90
	v_max_f32_e32 v89, 0, v95
	v_max_f32_e32 v91, 0, v91
	v_lshl_add_u64 v[96:97], s[36:37], 0, v[96:97]
	v_pk_mul_f32 v[92:93], v[92:93], v[92:93]
	v_pk_mul_f32 v[94:95], v[88:89], v[88:89]
	v_pk_mul_f32 v[102:103], v[90:91], v[90:91]
	v_pk_fma_f32 v[80:81], v[80:81], v[98:99], v[128:129] op_sel_hi:[1,0,1]
	v_lshl_add_u64 v[96:97], v[96:97], 0, v[164:165]
	v_cvt_pk_bf16_f32 v88, v92, v93
	v_cvt_pk_bf16_f32 v89, v94, v95
	v_cvt_pk_bf16_f32 v90, v100, v101
	v_cvt_pk_bf16_f32 v91, v102, v103
	v_pk_fma_f32 v[86:87], v[86:87], v[98:99], v[134:135] op_sel_hi:[1,0,1]
	v_pk_fma_f32 v[84:85], v[84:85], v[98:99], v[132:133] op_sel_hi:[1,0,1]
	v_pk_fma_f32 v[82:83], v[82:83], v[98:99], v[130:131] op_sel_hi:[1,0,1]
	v_max_f32_e32 v80, 0, v80
	v_max_f32_e32 v81, 0, v81
	ds_write_b128 v248, v[88:91]
	v_lshl_add_u64 v[252:253], v[96:97], 0, v[250:251]
	v_max_f32_e32 v84, 0, v84
	v_max_f32_e32 v85, 0, v85
	v_pk_mul_f32 v[88:89], v[80:81], v[80:81]
	v_max_f32_e32 v80, 0, v86
	v_max_f32_e32 v82, 0, v82
	v_max_f32_e32 v81, 0, v87
	v_max_f32_e32 v83, 0, v83
	v_pk_mul_f32 v[84:85], v[84:85], v[84:85]
	v_pk_mul_f32 v[86:87], v[80:81], v[80:81]
	v_pk_mul_f32 v[90:91], v[82:83], v[82:83]
	v_cvt_pk_bf16_f32 v80, v84, v85
	v_cvt_pk_bf16_f32 v81, v86, v87
	v_cvt_pk_bf16_f32 v82, v88, v89
	v_cvt_pk_bf16_f32 v83, v90, v91
	ds_write_b128 v248, v[80:83] offset:1024
	v_lshl_add_u64 v[254:255], v[96:97], 0, v[250:251]
	s_waitcnt lgkmcnt(0)
	ds_read_b128 v[244:247], v249
	ds_read_b128 v[80:83], v249 offset:1024
	s_waitcnt lgkmcnt(1)
	global_store_dwordx4 v[252:253], v[244:247], off
	s_waitcnt lgkmcnt(0)
	global_store_dwordx4 v[254:255], v[80:83], off offset:256
	s_mov_b64 s[38:39], s[30:31]
	s_mov_b32 s25, s58
	v_mov_b32_e32 v82, v99
	v_or_b32_e32 v80, 48, v162
	v_pk_fma_f32 v[72:73], v[72:73], v[82:83], v[136:137] op_sel_hi:[1,0,1]
	v_ashrrev_i32_e32 v81, 31, v80
	v_pk_fma_f32 v[78:79], v[78:79], v[82:83], v[142:143] op_sel_hi:[1,0,1]
	v_pk_fma_f32 v[76:77], v[76:77], v[82:83], v[140:141] op_sel_hi:[1,0,1]
	v_pk_fma_f32 v[74:75], v[74:75], v[82:83], v[138:139] op_sel_hi:[1,0,1]
	v_max_f32_e32 v72, 0, v72
	v_max_f32_e32 v73, 0, v73
	v_lshlrev_b64 v[80:81], 13, v[80:81]
	v_max_f32_e32 v76, 0, v76
	v_max_f32_e32 v77, 0, v77
	v_pk_mul_f32 v[84:85], v[72:73], v[72:73]
	v_max_f32_e32 v72, 0, v78
	v_max_f32_e32 v74, 0, v74
	v_max_f32_e32 v73, 0, v79
	v_max_f32_e32 v75, 0, v75
	v_lshl_add_u64 v[80:81], s[36:37], 0, v[80:81]
	v_pk_mul_f32 v[76:77], v[76:77], v[76:77]
	v_pk_mul_f32 v[78:79], v[72:73], v[72:73]
	v_pk_mul_f32 v[86:87], v[74:75], v[74:75]
	v_pk_fma_f32 v[68:69], v[68:69], v[82:83], v[132:133] op_sel_hi:[1,0,1]
	v_pk_fma_f32 v[64:65], v[64:65], v[82:83], v[128:129] op_sel_hi:[1,0,1]
	v_lshl_add_u64 v[80:81], v[80:81], 0, v[164:165]
	v_cvt_pk_bf16_f32 v72, v76, v77
	v_cvt_pk_bf16_f32 v73, v78, v79
	v_cvt_pk_bf16_f32 v74, v84, v85
	v_cvt_pk_bf16_f32 v75, v86, v87
	v_pk_fma_f32 v[70:71], v[70:71], v[82:83], v[134:135] op_sel_hi:[1,0,1]
	v_max_f32_e32 v68, 0, v68
	v_max_f32_e32 v64, 0, v64
	v_max_f32_e32 v69, 0, v69
	v_max_f32_e32 v65, 0, v65
	ds_write_b128 v248, v[72:75]
	v_lshl_add_u64 v[252:253], v[80:81], 0, v[250:251]
	v_pk_mul_f32 v[68:69], v[68:69], v[68:69]
	v_pk_fma_f32 v[66:67], v[66:67], v[82:83], v[130:131] op_sel_hi:[1,0,1]
	v_pk_mul_f32 v[72:73], v[64:65], v[64:65]
	v_max_f32_e32 v64, 0, v70
	v_max_f32_e32 v65, 0, v71
	v_pk_mul_f32 v[70:71], v[64:65], v[64:65]
	v_cvt_pk_bf16_f32 v64, v68, v69
	ds_read2_b32 v[68:69], v176 offset0:128 offset1:144
	v_max_f32_e32 v66, 0, v66
	v_max_f32_e32 v67, 0, v67
	v_pk_mul_f32 v[74:75], v[66:67], v[66:67]
	v_cvt_pk_bf16_f32 v65, v70, v71
	s_waitcnt lgkmcnt(0)
	v_pk_fma_f32 v[60:61], v[60:61], v[68:69], v[140:141] op_sel_hi:[1,0,1]
	v_pk_fma_f32 v[56:57], v[56:57], v[68:69], v[136:137] op_sel_hi:[1,0,1]
	v_cvt_pk_bf16_f32 v66, v72, v73
	v_cvt_pk_bf16_f32 v67, v74, v75
	v_pk_fma_f32 v[62:63], v[62:63], v[68:69], v[142:143] op_sel_hi:[1,0,1]
	v_pk_fma_f32 v[58:59], v[58:59], v[68:69], v[138:139] op_sel_hi:[1,0,1]
	v_max_f32_e32 v60, 0, v60
	v_max_f32_e32 v56, 0, v56
	v_max_f32_e32 v61, 0, v61
	v_max_f32_e32 v57, 0, v57
	ds_write_b128 v248, v[64:67] offset:1024
	v_lshl_add_u64 v[254:255], v[80:81], 0, v[250:251]
	s_waitcnt lgkmcnt(0)
	ds_read_b128 v[244:247], v249
	ds_read_b128 v[64:67], v249 offset:1024
	s_waitcnt lgkmcnt(1)
	global_store_dwordx4 v[252:253], v[244:247], off
	s_waitcnt lgkmcnt(0)
	global_store_dwordx4 v[254:255], v[64:67], off offset:256
	v_pk_mul_f32 v[60:61], v[60:61], v[60:61]
	v_max_f32_e32 v58, 0, v58
	v_pk_mul_f32 v[66:67], v[56:57], v[56:57]
	v_max_f32_e32 v56, 0, v62
	v_max_f32_e32 v57, 0, v63
	v_max_f32_e32 v59, 0, v59
	v_pk_mul_f32 v[62:63], v[56:57], v[56:57]
	v_pk_mul_f32 v[70:71], v[58:59], v[58:59]
	v_cvt_pk_bf16_f32 v56, v60, v61
	v_add_co_u32_e32 v60, vcc, s54, v160
	v_pk_fma_f32 v[48:49], v[48:49], v[68:69], v[128:129] op_sel_hi:[1,0,1]
	v_cvt_pk_bf16_f32 v57, v62, v63
	v_cvt_pk_bf16_f32 v58, v66, v67
	v_cvt_pk_bf16_f32 v59, v70, v71
	v_addc_co_u32_e32 v61, vcc, 0, v161, vcc
	v_pk_fma_f32 v[54:55], v[54:55], v[68:69], v[134:135] op_sel_hi:[1,0,1]
	v_pk_fma_f32 v[52:53], v[52:53], v[68:69], v[132:133] op_sel_hi:[1,0,1]
	v_pk_fma_f32 v[50:51], v[50:51], v[68:69], v[130:131] op_sel_hi:[1,0,1]
	v_max_f32_e32 v48, 0, v48
	v_max_f32_e32 v49, 0, v49
	ds_write_b128 v248, v[56:59]
	v_lshl_add_u64 v[252:253], v[60:61], 0, v[250:251]
	v_max_f32_e32 v52, 0, v52
	v_max_f32_e32 v53, 0, v53
	v_pk_mul_f32 v[56:57], v[48:49], v[48:49]
	v_max_f32_e32 v48, 0, v54
	v_max_f32_e32 v50, 0, v50
	v_max_f32_e32 v49, 0, v55
	v_max_f32_e32 v51, 0, v51
	v_pk_mul_f32 v[52:53], v[52:53], v[52:53]
	v_pk_mul_f32 v[54:55], v[48:49], v[48:49]
	v_pk_mul_f32 v[58:59], v[50:51], v[50:51]
	v_lshl_add_u64 v[64:65], v[160:161], 0, s[16:17]
	v_cvt_pk_bf16_f32 v48, v52, v53
	v_cvt_pk_bf16_f32 v49, v54, v55
	v_cvt_pk_bf16_f32 v50, v56, v57
	v_cvt_pk_bf16_f32 v51, v58, v59
	ds_write_b128 v248, v[48:51] offset:1024
	v_lshl_add_u64 v[254:255], v[64:65], 0, v[250:251]
	s_waitcnt lgkmcnt(0)
	ds_read_b128 v[244:247], v249
	ds_read_b128 v[48:51], v249 offset:1024
	s_waitcnt lgkmcnt(1)
	global_store_dwordx4 v[252:253], v[244:247], off
	s_waitcnt lgkmcnt(0)
	global_store_dwordx4 v[254:255], v[48:51], off offset:256
	s_mov_b64 s[36:37], s[28:29]
	v_readlane_b32 s65, v243, 2
	v_mov_b32_e32 v50, v69
	v_pk_fma_f32 v[44:45], v[44:45], v[50:51], v[140:141] op_sel_hi:[1,0,1]
	v_pk_fma_f32 v[40:41], v[40:41], v[50:51], v[136:137] op_sel_hi:[1,0,1]
	v_pk_fma_f32 v[46:47], v[46:47], v[50:51], v[142:143] op_sel_hi:[1,0,1]
	v_pk_fma_f32 v[42:43], v[42:43], v[50:51], v[138:139] op_sel_hi:[1,0,1]
	v_max_f32_e32 v44, 0, v44
	v_max_f32_e32 v40, 0, v40
	v_max_f32_e32 v45, 0, v45
	v_max_f32_e32 v41, 0, v41
	v_pk_mul_f32 v[44:45], v[44:45], v[44:45]
	v_pk_mul_f32 v[52:53], v[40:41], v[40:41]
	v_max_f32_e32 v40, 0, v46
	v_max_f32_e32 v42, 0, v42
	v_max_f32_e32 v41, 0, v47
	v_max_f32_e32 v43, 0, v43
	v_pk_mul_f32 v[46:47], v[40:41], v[40:41]
	v_pk_mul_f32 v[54:55], v[42:43], v[42:43]
	v_cvt_pk_bf16_f32 v40, v44, v45
	v_add_co_u32_e32 v44, vcc, s55, v160
	v_pk_fma_f32 v[36:37], v[36:37], v[50:51], v[132:133] op_sel_hi:[1,0,1]
	v_pk_fma_f32 v[32:33], v[32:33], v[50:51], v[128:129] op_sel_hi:[1,0,1]
	v_cvt_pk_bf16_f32 v41, v46, v47
	v_cvt_pk_bf16_f32 v42, v52, v53
	v_cvt_pk_bf16_f32 v43, v54, v55
	v_addc_co_u32_e32 v45, vcc, 0, v161, vcc
	v_pk_fma_f32 v[38:39], v[38:39], v[50:51], v[134:135] op_sel_hi:[1,0,1]
	v_max_f32_e32 v36, 0, v36
	v_max_f32_e32 v32, 0, v32
	v_max_f32_e32 v37, 0, v37
	v_max_f32_e32 v33, 0, v33
	ds_write_b128 v248, v[40:43]
	v_lshl_add_u64 v[252:253], v[44:45], 0, v[250:251]
	v_pk_mul_f32 v[36:37], v[36:37], v[36:37]
	v_pk_fma_f32 v[34:35], v[34:35], v[50:51], v[130:131] op_sel_hi:[1,0,1]
	v_pk_mul_f32 v[40:41], v[32:33], v[32:33]
	v_max_f32_e32 v32, 0, v38
	v_max_f32_e32 v33, 0, v39
	v_pk_mul_f32 v[38:39], v[32:33], v[32:33]
	v_cvt_pk_bf16_f32 v32, v36, v37
	ds_read2_b32 v[36:37], v176 offset0:160 offset1:176
	v_max_f32_e32 v34, 0, v34
	v_max_f32_e32 v35, 0, v35
	v_pk_mul_f32 v[42:43], v[34:35], v[34:35]
	v_lshl_add_u64 v[48:49], v[160:161], 0, s[18:19]
	s_waitcnt lgkmcnt(0)
	v_pk_fma_f32 v[28:29], v[28:29], v[36:37], v[140:141] op_sel_hi:[1,0,1]
	v_pk_fma_f32 v[24:25], v[24:25], v[36:37], v[136:137] op_sel_hi:[1,0,1]
	v_cvt_pk_bf16_f32 v33, v38, v39
	v_cvt_pk_bf16_f32 v34, v40, v41
	v_cvt_pk_bf16_f32 v35, v42, v43
	v_pk_fma_f32 v[30:31], v[30:31], v[36:37], v[142:143] op_sel_hi:[1,0,1]
	v_pk_fma_f32 v[26:27], v[26:27], v[36:37], v[138:139] op_sel_hi:[1,0,1]
	v_max_f32_e32 v28, 0, v28
	v_max_f32_e32 v24, 0, v24
	v_max_f32_e32 v29, 0, v29
	v_max_f32_e32 v25, 0, v25
	ds_write_b128 v248, v[32:35] offset:1024
	v_lshl_add_u64 v[254:255], v[48:49], 0, v[250:251]
	s_waitcnt lgkmcnt(0)
	ds_read_b128 v[244:247], v249
	ds_read_b128 v[32:35], v249 offset:1024
	s_waitcnt lgkmcnt(1)
	global_store_dwordx4 v[252:253], v[244:247], off
	s_waitcnt lgkmcnt(0)
	global_store_dwordx4 v[254:255], v[32:35], off offset:256
	v_pk_mul_f32 v[28:29], v[28:29], v[28:29]
	v_max_f32_e32 v26, 0, v26
	v_pk_mul_f32 v[34:35], v[24:25], v[24:25]
	v_max_f32_e32 v24, 0, v30
	v_max_f32_e32 v25, 0, v31
	v_max_f32_e32 v27, 0, v27
	v_pk_mul_f32 v[30:31], v[24:25], v[24:25]
	v_pk_mul_f32 v[38:39], v[26:27], v[26:27]
	v_cvt_pk_bf16_f32 v24, v28, v29
	v_add_co_u32_e32 v28, vcc, s56, v160
	v_pk_fma_f32 v[16:17], v[16:17], v[36:37], v[128:129] op_sel_hi:[1,0,1]
	v_cvt_pk_bf16_f32 v25, v30, v31
	v_cvt_pk_bf16_f32 v26, v34, v35
	v_cvt_pk_bf16_f32 v27, v38, v39
	v_addc_co_u32_e32 v29, vcc, 0, v161, vcc
	v_pk_fma_f32 v[22:23], v[22:23], v[36:37], v[134:135] op_sel_hi:[1,0,1]
	v_pk_fma_f32 v[20:21], v[20:21], v[36:37], v[132:133] op_sel_hi:[1,0,1]
	v_pk_fma_f32 v[18:19], v[18:19], v[36:37], v[130:131] op_sel_hi:[1,0,1]
	v_max_f32_e32 v16, 0, v16
	v_max_f32_e32 v17, 0, v17
	ds_write_b128 v248, v[24:27]
	v_lshl_add_u64 v[252:253], v[28:29], 0, v[250:251]
	v_max_f32_e32 v20, 0, v20
	v_max_f32_e32 v21, 0, v21
	v_pk_mul_f32 v[24:25], v[16:17], v[16:17]
	v_max_f32_e32 v16, 0, v22
	v_max_f32_e32 v18, 0, v18
	v_max_f32_e32 v17, 0, v23
	v_max_f32_e32 v19, 0, v19
	v_pk_mul_f32 v[20:21], v[20:21], v[20:21]
	v_pk_mul_f32 v[22:23], v[16:17], v[16:17]
	v_pk_mul_f32 v[26:27], v[18:19], v[18:19]
	v_lshl_add_u64 v[32:33], v[160:161], 0, s[20:21]
	v_cvt_pk_bf16_f32 v16, v20, v21
	v_cvt_pk_bf16_f32 v17, v22, v23
	v_cvt_pk_bf16_f32 v18, v24, v25
	v_cvt_pk_bf16_f32 v19, v26, v27
	ds_write_b128 v248, v[16:19] offset:1024
	v_lshl_add_u64 v[254:255], v[32:33], 0, v[250:251]
	s_waitcnt lgkmcnt(0)
	ds_read_b128 v[244:247], v249
	ds_read_b128 v[16:19], v249 offset:1024
	s_waitcnt lgkmcnt(1)
	global_store_dwordx4 v[252:253], v[244:247], off
	s_waitcnt lgkmcnt(0)
	global_store_dwordx4 v[254:255], v[16:19], off offset:256
	v_readlane_b32 s66, v243, 3
	v_readlane_b32 s67, v243, 4
	v_mov_b32_e32 v18, v37
	v_pk_fma_f32 v[12:13], v[12:13], v[18:19], v[140:141] op_sel_hi:[1,0,1]
	v_pk_fma_f32 v[8:9], v[8:9], v[18:19], v[136:137] op_sel_hi:[1,0,1]
	v_pk_fma_f32 v[14:15], v[14:15], v[18:19], v[142:143] op_sel_hi:[1,0,1]
	v_pk_fma_f32 v[10:11], v[10:11], v[18:19], v[138:139] op_sel_hi:[1,0,1]
	v_max_f32_e32 v12, 0, v12
	v_max_f32_e32 v8, 0, v8
	v_max_f32_e32 v13, 0, v13
	v_max_f32_e32 v9, 0, v9
	v_pk_mul_f32 v[12:13], v[12:13], v[12:13]
	v_pk_mul_f32 v[20:21], v[8:9], v[8:9]
	v_max_f32_e32 v8, 0, v14
	v_max_f32_e32 v10, 0, v10
	v_max_f32_e32 v9, 0, v15
	v_max_f32_e32 v11, 0, v11
	v_pk_mul_f32 v[14:15], v[8:9], v[8:9]
	v_pk_mul_f32 v[22:23], v[10:11], v[10:11]
	v_cvt_pk_bf16_f32 v8, v12, v13
	v_add_co_u32_e32 v12, vcc, s57, v160
	v_pk_fma_f32 v[0:1], v[0:1], v[18:19], v[128:129] op_sel_hi:[1,0,1]
	v_cvt_pk_bf16_f32 v9, v14, v15
	v_cvt_pk_bf16_f32 v10, v20, v21
	v_cvt_pk_bf16_f32 v11, v22, v23
	v_addc_co_u32_e32 v13, vcc, 0, v161, vcc
	v_pk_fma_f32 v[6:7], v[6:7], v[18:19], v[134:135] op_sel_hi:[1,0,1]
	v_pk_fma_f32 v[4:5], v[4:5], v[18:19], v[132:133] op_sel_hi:[1,0,1]
	v_pk_fma_f32 v[2:3], v[2:3], v[18:19], v[130:131] op_sel_hi:[1,0,1]
	v_max_f32_e32 v0, 0, v0
	v_max_f32_e32 v1, 0, v1
	ds_write_b128 v248, v[8:11]
	v_lshl_add_u64 v[252:253], v[12:13], 0, v[250:251]
	v_max_f32_e32 v4, 0, v4
	v_max_f32_e32 v5, 0, v5
	v_pk_mul_f32 v[8:9], v[0:1], v[0:1]
	v_max_f32_e32 v0, 0, v6
	v_max_f32_e32 v2, 0, v2
	v_max_f32_e32 v1, 0, v7
	v_max_f32_e32 v3, 0, v3
	v_pk_mul_f32 v[4:5], v[4:5], v[4:5]
	v_pk_mul_f32 v[6:7], v[0:1], v[0:1]
	v_pk_mul_f32 v[10:11], v[2:3], v[2:3]
	v_lshl_add_u64 v[16:17], v[160:161], 0, s[22:23]
	v_cvt_pk_bf16_f32 v0, v4, v5
	v_cvt_pk_bf16_f32 v1, v6, v7
	v_cvt_pk_bf16_f32 v2, v8, v9
	v_cvt_pk_bf16_f32 v3, v10, v11
	s_and_b64 vcc, exec, s[2:3]
	ds_write_b128 v248, v[0:3] offset:1024
	v_lshl_add_u64 v[254:255], v[16:17], 0, v[250:251]
	s_waitcnt lgkmcnt(0)
	ds_read_b128 v[244:247], v249
	ds_read_b128 v[0:3], v249 offset:1024
	s_waitcnt lgkmcnt(1)
	global_store_dwordx4 v[252:253], v[244:247], off
	s_waitcnt lgkmcnt(0)
	global_store_dwordx4 v[254:255], v[0:3], off offset:256
	s_cbranch_vccz .LBB0_1430
	s_waitcnt vmcnt(0)
	s_cmpk_gt_u32 s33, 0xff
	s_cbranch_scc1 .LBB0_1447
	s_barrier
